# P1 pair jobs: first k-slab of the workgroup's next pair job requested under the current job's epilogue (prologue/epilogue de-serialisation across jobs)
# speedup vs baseline: 1.0010x; 1.0010x over previous
; #define MFMA32(a, b, c) __builtin_amdgcn_mfma_f32_32x32x16_bf16((a), (b), (c), 0, 0, 0)
; template <bool SWAP, class Epi>
; DI void gemm_tile(const u16* __restrict__ A, int lda, const u16* __restrict__ Bw, int ldb, int K, char* lds, Epi epi) {
;     ...
;   const int lrow = tid >> 3, lkc = tid & 7;
;   u32x4 ra0[4], rb0[2], ra1[4], rb1[2];
;   const u16* ap = A + (size_t)lrow * lda + lkc * 8;
;   const u16* bp = Bw + (size_t)lrow * ldb + lkc * 8;
;   const int nk = K >> 6;
;   auto gload = [&](int kt, u32x4* ra, u32x4* rb) {
; #pragma unroll
;     for (int j = 0; j < 4; ++j) ra[j] = *(const u32x4*)(ap + (size_t)(64 * j) * lda + kt * 64);
; #pragma unroll
;     for (int j = 0; j < 2; ++j) rb[j] = *(const u32x4*)(bp + (size_t)(64 * j) * ldb + kt * 64);
;   };
;   auto lstore = [&](int st, const u32x4* ra, const u32x4* rb) {
;     char* base = lds + st * GEMM_STAGE;
; #pragma unroll
;     for (int j = 0; j < 4; ++j) *(u32x4*)(base + ((lrow + 64 * j) * 72 + lkc * 8) * 2) = ra[j];
; #pragma unroll
;     for (int j = 0; j < 2; ++j) *(u32x4*)(base + 36864 + ((lrow + 64 * j) * 72 + lkc * 8) * 2) = rb[j];
;   };
;   auto compute = [&](int st) {
;     const char* as = lds + st * GEMM_STAGE;
;     const char* bs = as + 36864;
; #pragma unroll
;     for (int ks = 0; ks < 4; ++ks) {
;       bf16x8 af[2], bfr[2];
; #pragma unroll
;       for (int mi = 0; mi < 2; ++mi) af[mi] = *(const bf16x8*)(as + ((wm * 64 + mi * 32 + r) * 72 + ks * 16 + 8 * h) * 2);
; #pragma unroll
;       for (int ni = 0; ni < 2; ++ni) bfr[ni] = *(const bf16x8*)(bs + ((wn * 64 + ni * 32 + r) * 72 + ks * 16 + 8 * h) * 2);
; #pragma unroll
;       for (int mi = 0; mi < 2; ++mi)
; #pragma unroll
;         for (int ni = 0; ni < 2; ++ni) {
;           if (SWAP) acc[mi][ni] = MFMA32(bfr[ni], af[mi], acc[mi][ni]);
;           else acc[mi][ni] = MFMA32(af[mi], bfr[ni], acc[mi][ni]);
;         }
;     }
;   };
;   gload(0, ra0, rb0);
;   lstore(0, ra0, rb0);
;   gload(1, ra1, rb1);
;   __syncthreads();
; DI void inproj_tile(const Params& p, int l, int mt, int nt, char* lds) {
;   const int tid = opaque_tid(), lane = tid & 63, w = tid >> 6, r = lane & 31, h = lane >> 5;
;   const int wm = w & 3, wn = w >> 2;
;   const int m0 = mt * 256;
;   const u16* A = p.Xb + (size_t)m0 * DM;
;   const u16* Bw = p.Wt_in + (size_t)(l & 1) * NIN * DM + (size_t)nt * 128 * DM;
.LBB0_320:
	v_readlane_b32 s0, v240, 17
	v_readlane_b32 s1, v240, 18
	s_andn2_b64 vcc, exec, s[0:1]
	s_lshl_b32 s0, s38, 4
	s_lshl_b32 s50, s38, 3
	v_writelane_b32 v238, s0, 45
	s_nop 1
	v_writelane_b32 v238, s1, 46
	s_cbranch_vccnz .LBB0_370
	s_bitcmp1_b32 s38, 0
	v_readlane_b32 s4, v241, 16
	s_cselect_b32 s0, 0xc00000, 0
	s_add_u32 s18, s4, s0
	v_readlane_b32 s0, v238, 45
	v_readlane_b32 s5, v241, 17
	s_addc_u32 s19, s5, 0
	s_mov_b32 s1, s61
	s_mov_b32 s2, s0
	v_writelane_b32 v238, s2, 45
	s_lshl_b64 s[0:1], s[0:1], 2
	v_readlane_b32 s6, v241, 42
	v_writelane_b32 v238, s3, 46
	v_readlane_b32 s7, v241, 43
	v_readlane_b32 s10, v241, 46
	s_add_u32 s20, s6, s0
	s_addc_u32 s21, s7, s1
	s_lshl_b32 s22, s10, 7
	v_readlane_b32 s23, v238, 17
	v_readlane_b32 s24, v238, 15
	v_readlane_b32 s25, v238, 16
	s_lshr_b32 s25, s25, 3
	s_mov_b32 s100, 0
	s_branch .LBB0_324
.Lpp_body:
	s_waitcnt lgkmcnt(0)
	s_barrier
	s_lshl_b32 s1, s0, 1
	s_cmp_gt_u32 s0, 1
	s_cselect_b32 s2, 4, 0
	s_add_i32 s2, s1, s2
	v_readlane_b32 s4, v241, 26
	v_readlane_b32 s5, v241, 27
	v_readlane_b32 s8, v241, 24
	v_readlane_b32 s9, v241, 25
	v_lshrrev_b32_e32 v0, 6, v152
	v_and_b32_e32 v1, 63, v152
	s_lshl_b32 s0, s26, 19
	s_add_u32 s4, s4, s0
	s_addc_u32 s5, s5, 0
	s_lshl_b32 s0, s2, 18
	s_add_u32 s6, s18, s0
	s_addc_u32 s7, s19, 0
	v_readfirstlane_b32 s3, v0
	s_lshl_b32 s0, s3, 16
	s_add_u32 s68, s4, s0
	s_addc_u32 s69, s5, 0
	s_add_u32 s70, s68, 0x3c00
	s_addc_u32 s71, s69, 0
	s_add_u32 s72, s70, 0x3c00
	s_addc_u32 s73, s71, 0
	s_add_u32 s74, s72, 0x3c00
	s_addc_u32 s75, s73, 0
	s_add_u32 s76, s6, s0
	s_addc_u32 s77, s7, 0
	s_add_u32 s78, s76, 0x3c00
	s_addc_u32 s79, s77, 0
	s_add_u32 s80, s78, 0x3c00
	s_addc_u32 s81, s79, 0
	s_add_u32 s82, s80, 0x3c00
	s_addc_u32 s83, s81, 0
	s_lshl_b32 s40, s3, 12
	s_add_i32 s44, s40, 0
	s_add_i32 s45, s40, 0x8000
	s_add_i32 s46, s40, 0x10000
	s_add_i32 s47, s40, 0x18000
	v_lshrrev_b32_e32 v2, 4, v1
	v_and_b32_e32 v0, 7, v1
	v_xor_b32_e32 v2, v2, v0
	v_lshlrev_b32_e32 v2, 4, v2
	v_lshrrev_b32_e32 v0, 3, v1
	v_lshlrev_b32_e32 v0, 11, v0
	v_add_u32_e32 v208, v2, v0
	v_xor_b32_e32 v209, 64, v208
	v_mov_b32_e32 v220, v208
	s_cmp_eq_u32 s100, 1
	s_cbranch_scc1 .Lpp_pfd
	s_mov_b32 m0, s44
	s_nop 0
	global_load_lds_dwordx4 v208, s[68:69]
	global_load_lds_dwordx4 v209, s[70:71] offset:1024
	global_load_lds_dwordx4 v208, s[72:73] offset:2048
	global_load_lds_dwordx4 v209, s[74:75] offset:3072
	s_mov_b32 m0, s46
	s_nop 0
	global_load_lds_dwordx4 v208, s[76:77]
	global_load_lds_dwordx4 v209, s[78:79] offset:1024
	global_load_lds_dwordx4 v208, s[80:81] offset:2048
	global_load_lds_dwordx4 v209, s[82:83] offset:3072
.Lpp_pfd:
	s_mov_b32 s100, 0
	v_add_u32_e32 v208, 0x80, v208
	v_add_u32_e32 v209, 0x80, v209
	v_and_b32_e32 v0, 31, v1
	v_lshrrev_b32_e32 v2, 1, v0
	v_and_b32_e32 v2, 7, v2
	v_lshrrev_b32_e32 v1, 5, v1
	v_xor_b32_e32 v2, v2, v1
	v_lshlrev_b32_e32 v0, 7, v0
	s_and_b32 s0, s3, 3
	s_lshr_b32 s1, s3, 2
	s_lshl_b32 s10, s0, 13
	s_lshl_b32 s11, s1, 13
	s_add_i32 s11, s11, 0x10000
	v_xor_b32_e32 v214, 0, v2
	v_lshl_add_u32 v214, v214, 4, v0
	v_add_u32_e32 v210, s10, v214
	v_add_u32_e32 v214, s11, v214
	v_xor_b32_e32 v215, 2, v2
	v_lshl_add_u32 v215, v215, 4, v0
	v_add_u32_e32 v211, s10, v215
	v_add_u32_e32 v215, s11, v215
	v_xor_b32_e32 v216, 4, v2
	v_lshl_add_u32 v216, v216, 4, v0
	v_add_u32_e32 v212, s10, v216
	v_add_u32_e32 v216, s11, v216
	v_xor_b32_e32 v217, 6, v2
	v_lshl_add_u32 v217, v217, 4, v0
	v_add_u32_e32 v213, s10, v217
	v_add_u32_e32 v217, s11, v217
	s_lshl_b32 s12, s26, 8
	s_lshl_b32 s0, s0, 6
	s_add_i32 s12, s12, s0
	v_lshrrev_b32_e32 v0, 7, v0
	v_add_u32_e32 v0, s12, v0
	v_mul_u32_u24_e32 v0, 0x2a00, v0
	s_lshl_b32 s12, s2, 8
	s_lshl_b32 s1, s1, 7
	s_add_i32 s12, s12, s1
	v_lshlrev_b32_e32 v1, 4, v1
	v_add3_u32 v218, v0, v1, s12
	v_add_u32_e32 v219, 0x54000, v218
	s_waitcnt vmcnt(0) lgkmcnt(0)
	s_barrier
	ds_read_b128 v[132:135], v210 offset:0
	ds_read_b128 v[136:139], v210 offset:4096
	ds_read_b128 v[140:143], v214 offset:0
	ds_read_b128 v[144:147], v214 offset:4096
	ds_read_b128 v[148:151], v214 offset:16384
	ds_read_b128 v[158:161], v214 offset:20480
	s_mov_b32 m0, s45
	s_nop 0
	global_load_lds_dwordx4 v208, s[68:69]
	global_load_lds_dwordx4 v209, s[70:71] offset:1024
	global_load_lds_dwordx4 v208, s[72:73] offset:2048
	global_load_lds_dwordx4 v209, s[74:75] offset:3072
	ds_read_b128 v[162:165], v211 offset:0
	ds_read_b128 v[168:171], v211 offset:4096
	ds_read_b128 v[172:175], v215 offset:0
	ds_read_b128 v[176:179], v215 offset:4096
	ds_read_b128 v[180:183], v215 offset:16384
	ds_read_b128 v[184:187], v215 offset:20480
	s_waitcnt lgkmcnt(6)
	v_mfma_f32_32x32x16_bf16 v[4:19], v[140:143], v[132:135], 0
	v_mfma_f32_32x32x16_bf16 v[68:83], v[140:143], v[136:139], 0
	v_mfma_f32_32x32x16_bf16 v[20:35], v[144:147], v[132:135], 0
	v_mfma_f32_32x32x16_bf16 v[84:99], v[144:147], v[136:139], 0
	v_mfma_f32_32x32x16_bf16 v[36:51], v[148:151], v[132:135], 0
	v_mfma_f32_32x32x16_bf16 v[100:115], v[148:151], v[136:139], 0
	v_mfma_f32_32x32x16_bf16 v[52:67], v[158:161], v[132:135], 0
	v_mfma_f32_32x32x16_bf16 v[116:131], v[158:161], v[136:139], 0
	s_mov_b32 m0, s47
	s_nop 0
	global_load_lds_dwordx4 v208, s[76:77]
	global_load_lds_dwordx4 v209, s[78:79] offset:1024
	global_load_lds_dwordx4 v208, s[80:81] offset:2048
	global_load_lds_dwordx4 v209, s[82:83] offset:3072
	v_add_u32_e32 v208, 0x80, v208
	v_add_u32_e32 v209, 0x80, v209
	ds_read_b128 v[132:135], v212 offset:0
	ds_read_b128 v[136:139], v212 offset:4096
	ds_read_b128 v[140:143], v216 offset:0
	ds_read_b128 v[144:147], v216 offset:4096
	ds_read_b128 v[148:151], v216 offset:16384
	ds_read_b128 v[158:161], v216 offset:20480
	s_waitcnt lgkmcnt(6)
; #define MFMA32(a, b, c) __builtin_amdgcn_mfma_f32_32x32x16_bf16((a), (b), (c), 0, 0, 0)
; template <bool SWAP, class Epi>
; DI void gemm_tile(const u16* __restrict__ A, int lda, const u16* __restrict__ Bw, int ldb, int K, char* lds, Epi epi) {
;     ...
;   auto compute = [&](int st) {
;     const char* as = lds + st * GEMM_STAGE;
;     const char* bs = as + 36864;
; #pragma unroll
;     for (int ks = 0; ks < 4; ++ks) {
;       bf16x8 af[2], bfr[2];
; #pragma unroll
;       for (int mi = 0; mi < 2; ++mi) af[mi] = *(const bf16x8*)(as + ((wm * 64 + mi * 32 + r) * 72 + ks * 16 + 8 * h) * 2);
; #pragma unroll
;       for (int ni = 0; ni < 2; ++ni) bfr[ni] = *(const bf16x8*)(bs + ((wn * 64 + ni * 32 + r) * 72 + ks * 16 + 8 * h) * 2);
; #pragma unroll
;       for (int mi = 0; mi < 2; ++mi)
; #pragma unroll
;         for (int ni = 0; ni < 2; ++ni) {
;           if (SWAP) acc[mi][ni] = MFMA32(bfr[ni], af[mi], acc[mi][ni]);
;           else acc[mi][ni] = MFMA32(af[mi], bfr[ni], acc[mi][ni]);
;         }
;     }
;   };
;   gload(0, ra0, rb0);
;   lstore(0, ra0, rb0);
;   gload(1, ra1, rb1);
;   __syncthreads();
;   for (int kt = 0; kt < nk; kt += 2) {
;     if (kt + 2 < nk) gload(kt + 2, ra0, rb0);
;     compute(0);
;     lstore(1, ra1, rb1);
;     __syncthreads();
;     if (kt + 3 < nk) gload(kt + 3, ra1, rb1);
;     compute(1);
;     if (kt + 2 < nk) lstore(0, ra0, rb0);
;     __syncthreads();
	v_mfma_f32_32x32x16_bf16 v[4:19], v[172:175], v[162:165], v[4:19]
	v_mfma_f32_32x32x16_bf16 v[68:83], v[172:175], v[168:171], v[68:83]
	v_mfma_f32_32x32x16_bf16 v[20:35], v[176:179], v[162:165], v[20:35]
	v_mfma_f32_32x32x16_bf16 v[84:99], v[176:179], v[168:171], v[84:99]
	v_mfma_f32_32x32x16_bf16 v[36:51], v[180:183], v[162:165], v[36:51]
	v_mfma_f32_32x32x16_bf16 v[100:115], v[180:183], v[168:171], v[100:115]
	v_mfma_f32_32x32x16_bf16 v[52:67], v[184:187], v[162:165], v[52:67]
	v_mfma_f32_32x32x16_bf16 v[116:131], v[184:187], v[168:171], v[116:131]
	ds_read_b128 v[162:165], v213 offset:0
	ds_read_b128 v[168:171], v213 offset:4096
	ds_read_b128 v[172:175], v217 offset:0
	ds_read_b128 v[176:179], v217 offset:4096
	ds_read_b128 v[180:183], v217 offset:16384
	ds_read_b128 v[184:187], v217 offset:20480
	s_waitcnt lgkmcnt(6)
	v_mfma_f32_32x32x16_bf16 v[4:19], v[140:143], v[132:135], v[4:19]
	v_mfma_f32_32x32x16_bf16 v[68:83], v[140:143], v[136:139], v[68:83]
	v_mfma_f32_32x32x16_bf16 v[20:35], v[144:147], v[132:135], v[20:35]
	v_mfma_f32_32x32x16_bf16 v[84:99], v[144:147], v[136:139], v[84:99]
	v_mfma_f32_32x32x16_bf16 v[36:51], v[148:151], v[132:135], v[36:51]
	v_mfma_f32_32x32x16_bf16 v[100:115], v[148:151], v[136:139], v[100:115]
	v_mfma_f32_32x32x16_bf16 v[52:67], v[158:161], v[132:135], v[52:67]
	v_mfma_f32_32x32x16_bf16 v[116:131], v[158:161], v[136:139], v[116:131]
	s_waitcnt lgkmcnt(0)
	v_mfma_f32_32x32x16_bf16 v[4:19], v[172:175], v[162:165], v[4:19]
	v_mfma_f32_32x32x16_bf16 v[68:83], v[172:175], v[168:171], v[68:83]
	v_mfma_f32_32x32x16_bf16 v[20:35], v[176:179], v[162:165], v[20:35]
	v_mfma_f32_32x32x16_bf16 v[84:99], v[176:179], v[168:171], v[84:99]
	v_mfma_f32_32x32x16_bf16 v[36:51], v[180:183], v[162:165], v[36:51]
	v_mfma_f32_32x32x16_bf16 v[100:115], v[180:183], v[168:171], v[100:115]
	v_mfma_f32_32x32x16_bf16 v[52:67], v[184:187], v[162:165], v[52:67]
	v_mfma_f32_32x32x16_bf16 v[116:131], v[184:187], v[168:171], v[116:131]
	s_waitcnt vmcnt(0) lgkmcnt(0)
	s_barrier
	ds_read_b128 v[132:135], v210 offset:32768
	ds_read_b128 v[136:139], v210 offset:36864
	ds_read_b128 v[140:143], v214 offset:32768
	ds_read_b128 v[144:147], v214 offset:36864
	ds_read_b128 v[148:151], v214 offset:49152
	ds_read_b128 v[158:161], v214 offset:53248
	s_mov_b32 m0, s44
	s_nop 0
	global_load_lds_dwordx4 v208, s[68:69]
	global_load_lds_dwordx4 v209, s[70:71] offset:1024
	global_load_lds_dwordx4 v208, s[72:73] offset:2048
	global_load_lds_dwordx4 v209, s[74:75] offset:3072
	ds_read_b128 v[162:165], v211 offset:32768
	ds_read_b128 v[168:171], v211 offset:36864
	ds_read_b128 v[172:175], v215 offset:32768
	ds_read_b128 v[176:179], v215 offset:36864
	ds_read_b128 v[180:183], v215 offset:49152
	ds_read_b128 v[184:187], v215 offset:53248
	s_waitcnt lgkmcnt(6)
	v_mfma_f32_32x32x16_bf16 v[4:19], v[140:143], v[132:135], v[4:19]
	v_mfma_f32_32x32x16_bf16 v[68:83], v[140:143], v[136:139], v[68:83]
	v_mfma_f32_32x32x16_bf16 v[20:35], v[144:147], v[132:135], v[20:35]
	v_mfma_f32_32x32x16_bf16 v[84:99], v[144:147], v[136:139], v[84:99]
	v_mfma_f32_32x32x16_bf16 v[36:51], v[148:151], v[132:135], v[36:51]
	v_mfma_f32_32x32x16_bf16 v[100:115], v[148:151], v[136:139], v[100:115]
	v_mfma_f32_32x32x16_bf16 v[52:67], v[158:161], v[132:135], v[52:67]
	v_mfma_f32_32x32x16_bf16 v[116:131], v[158:161], v[136:139], v[116:131]
	s_mov_b32 m0, s46
	s_nop 0
	global_load_lds_dwordx4 v208, s[76:77]
	global_load_lds_dwordx4 v209, s[78:79] offset:1024
	global_load_lds_dwordx4 v208, s[80:81] offset:2048
	global_load_lds_dwordx4 v209, s[82:83] offset:3072
	v_add_u32_e32 v208, 0x80, v208
	v_add_u32_e32 v209, 0x80, v209
	ds_read_b128 v[132:135], v212 offset:32768
	ds_read_b128 v[136:139], v212 offset:36864
	ds_read_b128 v[140:143], v216 offset:32768
	ds_read_b128 v[144:147], v216 offset:36864
	ds_read_b128 v[148:151], v216 offset:49152
	ds_read_b128 v[158:161], v216 offset:53248
	s_waitcnt lgkmcnt(6)
	v_mfma_f32_32x32x16_bf16 v[4:19], v[172:175], v[162:165], v[4:19]
	v_mfma_f32_32x32x16_bf16 v[68:83], v[172:175], v[168:171], v[68:83]
	v_mfma_f32_32x32x16_bf16 v[20:35], v[176:179], v[162:165], v[20:35]
	v_mfma_f32_32x32x16_bf16 v[84:99], v[176:179], v[168:171], v[84:99]
	v_mfma_f32_32x32x16_bf16 v[36:51], v[180:183], v[162:165], v[36:51]
	v_mfma_f32_32x32x16_bf16 v[100:115], v[180:183], v[168:171], v[100:115]
	v_mfma_f32_32x32x16_bf16 v[52:67], v[184:187], v[162:165], v[52:67]
	v_mfma_f32_32x32x16_bf16 v[116:131], v[184:187], v[168:171], v[116:131]
	ds_read_b128 v[162:165], v213 offset:32768
	ds_read_b128 v[168:171], v213 offset:36864
	ds_read_b128 v[172:175], v217 offset:32768
	ds_read_b128 v[176:179], v217 offset:36864
	ds_read_b128 v[180:183], v217 offset:49152
	ds_read_b128 v[184:187], v217 offset:53248
	s_waitcnt lgkmcnt(6)
	v_mfma_f32_32x32x16_bf16 v[4:19], v[140:143], v[132:135], v[4:19]
	v_mfma_f32_32x32x16_bf16 v[68:83], v[140:143], v[136:139], v[68:83]
	v_mfma_f32_32x32x16_bf16 v[20:35], v[144:147], v[132:135], v[20:35]
	v_mfma_f32_32x32x16_bf16 v[84:99], v[144:147], v[136:139], v[84:99]
	v_mfma_f32_32x32x16_bf16 v[36:51], v[148:151], v[132:135], v[36:51]
	v_mfma_f32_32x32x16_bf16 v[100:115], v[148:151], v[136:139], v[100:115]
	v_mfma_f32_32x32x16_bf16 v[52:67], v[158:161], v[132:135], v[52:67]
	v_mfma_f32_32x32x16_bf16 v[116:131], v[158:161], v[136:139], v[116:131]
	s_waitcnt lgkmcnt(0)
	v_mfma_f32_32x32x16_bf16 v[4:19], v[172:175], v[162:165], v[4:19]
	v_mfma_f32_32x32x16_bf16 v[68:83], v[172:175], v[168:171], v[68:83]
	v_mfma_f32_32x32x16_bf16 v[20:35], v[176:179], v[162:165], v[20:35]
	v_mfma_f32_32x32x16_bf16 v[84:99], v[176:179], v[168:171], v[84:99]
	v_mfma_f32_32x32x16_bf16 v[36:51], v[180:183], v[162:165], v[36:51]
	v_mfma_f32_32x32x16_bf16 v[100:115], v[180:183], v[168:171], v[100:115]
	v_mfma_f32_32x32x16_bf16 v[52:67], v[184:187], v[162:165], v[52:67]
	v_mfma_f32_32x32x16_bf16 v[116:131], v[184:187], v[168:171], v[116:131]
	s_waitcnt vmcnt(0) lgkmcnt(0)
	s_barrier
; #define MFMA32(a, b, c) __builtin_amdgcn_mfma_f32_32x32x16_bf16((a), (b), (c), 0, 0, 0)
; template <bool SWAP, class Epi>
; DI void gemm_tile(const u16* __restrict__ A, int lda, const u16* __restrict__ Bw, int ldb, int K, char* lds, Epi epi) {
;     ...
;   auto compute = [&](int st) {
;     const char* as = lds + st * GEMM_STAGE;
;     const char* bs = as + 36864;
; #pragma unroll
;     for (int ks = 0; ks < 4; ++ks) {
;       bf16x8 af[2], bfr[2];
; #pragma unroll
;       for (int mi = 0; mi < 2; ++mi) af[mi] = *(const bf16x8*)(as + ((wm * 64 + mi * 32 + r) * 72 + ks * 16 + 8 * h) * 2);
; #pragma unroll
;       for (int ni = 0; ni < 2; ++ni) bfr[ni] = *(const bf16x8*)(bs + ((wn * 64 + ni * 32 + r) * 72 + ks * 16 + 8 * h) * 2);
; #pragma unroll
;       for (int mi = 0; mi < 2; ++mi)
; #pragma unroll
;         for (int ni = 0; ni < 2; ++ni) {
;           if (SWAP) acc[mi][ni] = MFMA32(bfr[ni], af[mi], acc[mi][ni]);
;           else acc[mi][ni] = MFMA32(af[mi], bfr[ni], acc[mi][ni]);
;         }
;     }
;   };
;   gload(0, ra0, rb0);
;   lstore(0, ra0, rb0);
;   gload(1, ra1, rb1);
;   __syncthreads();
;   for (int kt = 0; kt < nk; kt += 2) {
;     if (kt + 2 < nk) gload(kt + 2, ra0, rb0);
;     compute(0);
;     lstore(1, ra1, rb1);
;     __syncthreads();
;     if (kt + 3 < nk) gload(kt + 3, ra1, rb1);
;     compute(1);
;     if (kt + 2 < nk) lstore(0, ra0, rb0);
;     __syncthreads();
	ds_read_b128 v[132:135], v210 offset:0
	ds_read_b128 v[136:139], v210 offset:4096
	ds_read_b128 v[140:143], v214 offset:0
	ds_read_b128 v[144:147], v214 offset:4096
	ds_read_b128 v[148:151], v214 offset:16384
	ds_read_b128 v[158:161], v214 offset:20480
	s_mov_b32 m0, s45
	s_nop 0
	global_load_lds_dwordx4 v208, s[68:69]
	global_load_lds_dwordx4 v209, s[70:71] offset:1024
	global_load_lds_dwordx4 v208, s[72:73] offset:2048
	global_load_lds_dwordx4 v209, s[74:75] offset:3072
	ds_read_b128 v[162:165], v211 offset:0
	ds_read_b128 v[168:171], v211 offset:4096
	ds_read_b128 v[172:175], v215 offset:0
	ds_read_b128 v[176:179], v215 offset:4096
	ds_read_b128 v[180:183], v215 offset:16384
	ds_read_b128 v[184:187], v215 offset:20480
	s_waitcnt lgkmcnt(6)
	v_mfma_f32_32x32x16_bf16 v[4:19], v[140:143], v[132:135], v[4:19]
	v_mfma_f32_32x32x16_bf16 v[68:83], v[140:143], v[136:139], v[68:83]
	v_mfma_f32_32x32x16_bf16 v[20:35], v[144:147], v[132:135], v[20:35]
	v_mfma_f32_32x32x16_bf16 v[84:99], v[144:147], v[136:139], v[84:99]
	v_mfma_f32_32x32x16_bf16 v[36:51], v[148:151], v[132:135], v[36:51]
	v_mfma_f32_32x32x16_bf16 v[100:115], v[148:151], v[136:139], v[100:115]
	v_mfma_f32_32x32x16_bf16 v[52:67], v[158:161], v[132:135], v[52:67]
	v_mfma_f32_32x32x16_bf16 v[116:131], v[158:161], v[136:139], v[116:131]
	s_mov_b32 m0, s47
	s_nop 0
	global_load_lds_dwordx4 v208, s[76:77]
	global_load_lds_dwordx4 v209, s[78:79] offset:1024
	global_load_lds_dwordx4 v208, s[80:81] offset:2048
	global_load_lds_dwordx4 v209, s[82:83] offset:3072
	v_add_u32_e32 v208, 0x80, v208
	v_add_u32_e32 v209, 0x80, v209
	ds_read_b128 v[132:135], v212 offset:0
	ds_read_b128 v[136:139], v212 offset:4096
	ds_read_b128 v[140:143], v216 offset:0
	ds_read_b128 v[144:147], v216 offset:4096
	ds_read_b128 v[148:151], v216 offset:16384
	ds_read_b128 v[158:161], v216 offset:20480
	s_waitcnt lgkmcnt(6)
	v_mfma_f32_32x32x16_bf16 v[4:19], v[172:175], v[162:165], v[4:19]
	v_mfma_f32_32x32x16_bf16 v[68:83], v[172:175], v[168:171], v[68:83]
	v_mfma_f32_32x32x16_bf16 v[20:35], v[176:179], v[162:165], v[20:35]
	v_mfma_f32_32x32x16_bf16 v[84:99], v[176:179], v[168:171], v[84:99]
	v_mfma_f32_32x32x16_bf16 v[36:51], v[180:183], v[162:165], v[36:51]
	v_mfma_f32_32x32x16_bf16 v[100:115], v[180:183], v[168:171], v[100:115]
	v_mfma_f32_32x32x16_bf16 v[52:67], v[184:187], v[162:165], v[52:67]
	v_mfma_f32_32x32x16_bf16 v[116:131], v[184:187], v[168:171], v[116:131]
	ds_read_b128 v[162:165], v213 offset:0
	ds_read_b128 v[168:171], v213 offset:4096
	ds_read_b128 v[172:175], v217 offset:0
	ds_read_b128 v[176:179], v217 offset:4096
	ds_read_b128 v[180:183], v217 offset:16384
	ds_read_b128 v[184:187], v217 offset:20480
	s_waitcnt lgkmcnt(6)
	v_mfma_f32_32x32x16_bf16 v[4:19], v[140:143], v[132:135], v[4:19]
	v_mfma_f32_32x32x16_bf16 v[68:83], v[140:143], v[136:139], v[68:83]
	v_mfma_f32_32x32x16_bf16 v[20:35], v[144:147], v[132:135], v[20:35]
	v_mfma_f32_32x32x16_bf16 v[84:99], v[144:147], v[136:139], v[84:99]
	v_mfma_f32_32x32x16_bf16 v[36:51], v[148:151], v[132:135], v[36:51]
	v_mfma_f32_32x32x16_bf16 v[100:115], v[148:151], v[136:139], v[100:115]
	v_mfma_f32_32x32x16_bf16 v[52:67], v[158:161], v[132:135], v[52:67]
	v_mfma_f32_32x32x16_bf16 v[116:131], v[158:161], v[136:139], v[116:131]
	s_waitcnt lgkmcnt(0)
	v_mfma_f32_32x32x16_bf16 v[4:19], v[172:175], v[162:165], v[4:19]
	v_mfma_f32_32x32x16_bf16 v[68:83], v[172:175], v[168:171], v[68:83]
	v_mfma_f32_32x32x16_bf16 v[20:35], v[176:179], v[162:165], v[20:35]
	v_mfma_f32_32x32x16_bf16 v[84:99], v[176:179], v[168:171], v[84:99]
	v_mfma_f32_32x32x16_bf16 v[36:51], v[180:183], v[162:165], v[36:51]
	v_mfma_f32_32x32x16_bf16 v[100:115], v[180:183], v[168:171], v[100:115]
	v_mfma_f32_32x32x16_bf16 v[52:67], v[184:187], v[162:165], v[52:67]
	v_mfma_f32_32x32x16_bf16 v[116:131], v[184:187], v[168:171], v[116:131]
	s_waitcnt vmcnt(0) lgkmcnt(0)
	s_barrier
	ds_read_b128 v[132:135], v210 offset:32768
	ds_read_b128 v[136:139], v210 offset:36864
	ds_read_b128 v[140:143], v214 offset:32768
	ds_read_b128 v[144:147], v214 offset:36864
	ds_read_b128 v[148:151], v214 offset:49152
	ds_read_b128 v[158:161], v214 offset:53248
	s_mov_b32 m0, s44
	s_nop 0
	global_load_lds_dwordx4 v208, s[68:69]
	global_load_lds_dwordx4 v209, s[70:71] offset:1024
	global_load_lds_dwordx4 v208, s[72:73] offset:2048
	global_load_lds_dwordx4 v209, s[74:75] offset:3072
	ds_read_b128 v[162:165], v211 offset:32768
	ds_read_b128 v[168:171], v211 offset:36864
	ds_read_b128 v[172:175], v215 offset:32768
	ds_read_b128 v[176:179], v215 offset:36864
	ds_read_b128 v[180:183], v215 offset:49152
	ds_read_b128 v[184:187], v215 offset:53248
	s_waitcnt lgkmcnt(6)
	v_mfma_f32_32x32x16_bf16 v[4:19], v[140:143], v[132:135], v[4:19]
	v_mfma_f32_32x32x16_bf16 v[68:83], v[140:143], v[136:139], v[68:83]
	v_mfma_f32_32x32x16_bf16 v[20:35], v[144:147], v[132:135], v[20:35]
	v_mfma_f32_32x32x16_bf16 v[84:99], v[144:147], v[136:139], v[84:99]
	v_mfma_f32_32x32x16_bf16 v[36:51], v[148:151], v[132:135], v[36:51]
	v_mfma_f32_32x32x16_bf16 v[100:115], v[148:151], v[136:139], v[100:115]
	v_mfma_f32_32x32x16_bf16 v[52:67], v[158:161], v[132:135], v[52:67]
	v_mfma_f32_32x32x16_bf16 v[116:131], v[158:161], v[136:139], v[116:131]
	s_mov_b32 m0, s46
	s_nop 0
	global_load_lds_dwordx4 v208, s[76:77]
	global_load_lds_dwordx4 v209, s[78:79] offset:1024
	global_load_lds_dwordx4 v208, s[80:81] offset:2048
	global_load_lds_dwordx4 v209, s[82:83] offset:3072
	v_add_u32_e32 v208, 0x80, v208
	v_add_u32_e32 v209, 0x80, v209
	ds_read_b128 v[132:135], v212 offset:32768
	ds_read_b128 v[136:139], v212 offset:36864
	ds_read_b128 v[140:143], v216 offset:32768
	ds_read_b128 v[144:147], v216 offset:36864
	ds_read_b128 v[148:151], v216 offset:49152
	ds_read_b128 v[158:161], v216 offset:53248
	s_waitcnt lgkmcnt(6)
; #define MFMA32(a, b, c) __builtin_amdgcn_mfma_f32_32x32x16_bf16((a), (b), (c), 0, 0, 0)
; template <bool SWAP, class Epi>
; DI void gemm_tile(const u16* __restrict__ A, int lda, const u16* __restrict__ Bw, int ldb, int K, char* lds, Epi epi) {
;     ...
;   auto compute = [&](int st) {
;     const char* as = lds + st * GEMM_STAGE;
;     const char* bs = as + 36864;
; #pragma unroll
;     for (int ks = 0; ks < 4; ++ks) {
;       bf16x8 af[2], bfr[2];
; #pragma unroll
;       for (int mi = 0; mi < 2; ++mi) af[mi] = *(const bf16x8*)(as + ((wm * 64 + mi * 32 + r) * 72 + ks * 16 + 8 * h) * 2);
; #pragma unroll
;       for (int ni = 0; ni < 2; ++ni) bfr[ni] = *(const bf16x8*)(bs + ((wn * 64 + ni * 32 + r) * 72 + ks * 16 + 8 * h) * 2);
; #pragma unroll
;       for (int mi = 0; mi < 2; ++mi)
; #pragma unroll
;         for (int ni = 0; ni < 2; ++ni) {
;           if (SWAP) acc[mi][ni] = MFMA32(bfr[ni], af[mi], acc[mi][ni]);
;           else acc[mi][ni] = MFMA32(af[mi], bfr[ni], acc[mi][ni]);
;         }
;     }
;   };
;   gload(0, ra0, rb0);
;   lstore(0, ra0, rb0);
;   gload(1, ra1, rb1);
;   __syncthreads();
;   for (int kt = 0; kt < nk; kt += 2) {
;     if (kt + 2 < nk) gload(kt + 2, ra0, rb0);
;     compute(0);
;     lstore(1, ra1, rb1);
;     __syncthreads();
;     if (kt + 3 < nk) gload(kt + 3, ra1, rb1);
;     compute(1);
;     if (kt + 2 < nk) lstore(0, ra0, rb0);
;     __syncthreads();
	v_mfma_f32_32x32x16_bf16 v[4:19], v[172:175], v[162:165], v[4:19]
	v_mfma_f32_32x32x16_bf16 v[68:83], v[172:175], v[168:171], v[68:83]
	v_mfma_f32_32x32x16_bf16 v[20:35], v[176:179], v[162:165], v[20:35]
	v_mfma_f32_32x32x16_bf16 v[84:99], v[176:179], v[168:171], v[84:99]
	v_mfma_f32_32x32x16_bf16 v[36:51], v[180:183], v[162:165], v[36:51]
	v_mfma_f32_32x32x16_bf16 v[100:115], v[180:183], v[168:171], v[100:115]
	v_mfma_f32_32x32x16_bf16 v[52:67], v[184:187], v[162:165], v[52:67]
	v_mfma_f32_32x32x16_bf16 v[116:131], v[184:187], v[168:171], v[116:131]
	ds_read_b128 v[162:165], v213 offset:32768
	ds_read_b128 v[168:171], v213 offset:36864
	ds_read_b128 v[172:175], v217 offset:32768
	ds_read_b128 v[176:179], v217 offset:36864
	ds_read_b128 v[180:183], v217 offset:49152
	ds_read_b128 v[184:187], v217 offset:53248
	s_waitcnt lgkmcnt(6)
	v_mfma_f32_32x32x16_bf16 v[4:19], v[140:143], v[132:135], v[4:19]
	v_mfma_f32_32x32x16_bf16 v[68:83], v[140:143], v[136:139], v[68:83]
	v_mfma_f32_32x32x16_bf16 v[20:35], v[144:147], v[132:135], v[20:35]
	v_mfma_f32_32x32x16_bf16 v[84:99], v[144:147], v[136:139], v[84:99]
	v_mfma_f32_32x32x16_bf16 v[36:51], v[148:151], v[132:135], v[36:51]
	v_mfma_f32_32x32x16_bf16 v[100:115], v[148:151], v[136:139], v[100:115]
	v_mfma_f32_32x32x16_bf16 v[52:67], v[158:161], v[132:135], v[52:67]
	v_mfma_f32_32x32x16_bf16 v[116:131], v[158:161], v[136:139], v[116:131]
	s_waitcnt lgkmcnt(0)
	v_mfma_f32_32x32x16_bf16 v[4:19], v[172:175], v[162:165], v[4:19]
	v_mfma_f32_32x32x16_bf16 v[68:83], v[172:175], v[168:171], v[68:83]
	v_mfma_f32_32x32x16_bf16 v[20:35], v[176:179], v[162:165], v[20:35]
	v_mfma_f32_32x32x16_bf16 v[84:99], v[176:179], v[168:171], v[84:99]
	v_mfma_f32_32x32x16_bf16 v[36:51], v[180:183], v[162:165], v[36:51]
	v_mfma_f32_32x32x16_bf16 v[100:115], v[180:183], v[168:171], v[100:115]
	v_mfma_f32_32x32x16_bf16 v[52:67], v[184:187], v[162:165], v[52:67]
	v_mfma_f32_32x32x16_bf16 v[116:131], v[184:187], v[168:171], v[116:131]
	s_waitcnt vmcnt(0) lgkmcnt(0)
	s_barrier
	ds_read_b128 v[132:135], v210 offset:0
	ds_read_b128 v[136:139], v210 offset:4096
	ds_read_b128 v[140:143], v214 offset:0
	ds_read_b128 v[144:147], v214 offset:4096
	ds_read_b128 v[148:151], v214 offset:16384
	ds_read_b128 v[158:161], v214 offset:20480
	s_mov_b32 m0, s45
	s_nop 0
	global_load_lds_dwordx4 v208, s[68:69]
	global_load_lds_dwordx4 v209, s[70:71] offset:1024
	global_load_lds_dwordx4 v208, s[72:73] offset:2048
	global_load_lds_dwordx4 v209, s[74:75] offset:3072
	ds_read_b128 v[162:165], v211 offset:0
	ds_read_b128 v[168:171], v211 offset:4096
	ds_read_b128 v[172:175], v215 offset:0
	ds_read_b128 v[176:179], v215 offset:4096
	ds_read_b128 v[180:183], v215 offset:16384
	ds_read_b128 v[184:187], v215 offset:20480
	s_waitcnt lgkmcnt(6)
	v_mfma_f32_32x32x16_bf16 v[4:19], v[140:143], v[132:135], v[4:19]
	v_mfma_f32_32x32x16_bf16 v[68:83], v[140:143], v[136:139], v[68:83]
	v_mfma_f32_32x32x16_bf16 v[20:35], v[144:147], v[132:135], v[20:35]
	v_mfma_f32_32x32x16_bf16 v[84:99], v[144:147], v[136:139], v[84:99]
	v_mfma_f32_32x32x16_bf16 v[36:51], v[148:151], v[132:135], v[36:51]
	v_mfma_f32_32x32x16_bf16 v[100:115], v[148:151], v[136:139], v[100:115]
	v_mfma_f32_32x32x16_bf16 v[52:67], v[158:161], v[132:135], v[52:67]
	v_mfma_f32_32x32x16_bf16 v[116:131], v[158:161], v[136:139], v[116:131]
	s_mov_b32 m0, s47
	s_nop 0
	global_load_lds_dwordx4 v208, s[76:77]
	global_load_lds_dwordx4 v209, s[78:79] offset:1024
	global_load_lds_dwordx4 v208, s[80:81] offset:2048
	global_load_lds_dwordx4 v209, s[82:83] offset:3072
	v_add_u32_e32 v208, 0x80, v208
	v_add_u32_e32 v209, 0x80, v209
	ds_read_b128 v[132:135], v212 offset:0
	ds_read_b128 v[136:139], v212 offset:4096
	ds_read_b128 v[140:143], v216 offset:0
	ds_read_b128 v[144:147], v216 offset:4096
	ds_read_b128 v[148:151], v216 offset:16384
	ds_read_b128 v[158:161], v216 offset:20480
	s_waitcnt lgkmcnt(6)
	v_mfma_f32_32x32x16_bf16 v[4:19], v[172:175], v[162:165], v[4:19]
	v_mfma_f32_32x32x16_bf16 v[68:83], v[172:175], v[168:171], v[68:83]
	v_mfma_f32_32x32x16_bf16 v[20:35], v[176:179], v[162:165], v[20:35]
	v_mfma_f32_32x32x16_bf16 v[84:99], v[176:179], v[168:171], v[84:99]
	v_mfma_f32_32x32x16_bf16 v[36:51], v[180:183], v[162:165], v[36:51]
	v_mfma_f32_32x32x16_bf16 v[100:115], v[180:183], v[168:171], v[100:115]
	v_mfma_f32_32x32x16_bf16 v[52:67], v[184:187], v[162:165], v[52:67]
	v_mfma_f32_32x32x16_bf16 v[116:131], v[184:187], v[168:171], v[116:131]
	ds_read_b128 v[162:165], v213 offset:0
	ds_read_b128 v[168:171], v213 offset:4096
	ds_read_b128 v[172:175], v217 offset:0
	ds_read_b128 v[176:179], v217 offset:4096
	ds_read_b128 v[180:183], v217 offset:16384
	ds_read_b128 v[184:187], v217 offset:20480
	s_waitcnt lgkmcnt(6)
	v_mfma_f32_32x32x16_bf16 v[4:19], v[140:143], v[132:135], v[4:19]
	v_mfma_f32_32x32x16_bf16 v[68:83], v[140:143], v[136:139], v[68:83]
	v_mfma_f32_32x32x16_bf16 v[20:35], v[144:147], v[132:135], v[20:35]
	v_mfma_f32_32x32x16_bf16 v[84:99], v[144:147], v[136:139], v[84:99]
	v_mfma_f32_32x32x16_bf16 v[36:51], v[148:151], v[132:135], v[36:51]
	v_mfma_f32_32x32x16_bf16 v[100:115], v[148:151], v[136:139], v[100:115]
	v_mfma_f32_32x32x16_bf16 v[52:67], v[158:161], v[132:135], v[52:67]
	v_mfma_f32_32x32x16_bf16 v[116:131], v[158:161], v[136:139], v[116:131]
	s_waitcnt lgkmcnt(0)
	v_mfma_f32_32x32x16_bf16 v[4:19], v[172:175], v[162:165], v[4:19]
	v_mfma_f32_32x32x16_bf16 v[68:83], v[172:175], v[168:171], v[68:83]
	v_mfma_f32_32x32x16_bf16 v[20:35], v[176:179], v[162:165], v[20:35]
	v_mfma_f32_32x32x16_bf16 v[84:99], v[176:179], v[168:171], v[84:99]
	v_mfma_f32_32x32x16_bf16 v[36:51], v[180:183], v[162:165], v[36:51]
	v_mfma_f32_32x32x16_bf16 v[100:115], v[180:183], v[168:171], v[100:115]
	v_mfma_f32_32x32x16_bf16 v[52:67], v[184:187], v[162:165], v[52:67]
	v_mfma_f32_32x32x16_bf16 v[116:131], v[184:187], v[168:171], v[116:131]
	s_waitcnt vmcnt(0) lgkmcnt(0)
	s_barrier
; #define MFMA32(a, b, c) __builtin_amdgcn_mfma_f32_32x32x16_bf16((a), (b), (c), 0, 0, 0)
; template <bool SWAP, class Epi>
; DI void gemm_tile(const u16* __restrict__ A, int lda, const u16* __restrict__ Bw, int ldb, int K, char* lds, Epi epi) {
;     ...
;   auto compute = [&](int st) {
;     const char* as = lds + st * GEMM_STAGE;
;     const char* bs = as + 36864;
; #pragma unroll
;     for (int ks = 0; ks < 4; ++ks) {
;       bf16x8 af[2], bfr[2];
; #pragma unroll
;       for (int mi = 0; mi < 2; ++mi) af[mi] = *(const bf16x8*)(as + ((wm * 64 + mi * 32 + r) * 72 + ks * 16 + 8 * h) * 2);
; #pragma unroll
;       for (int ni = 0; ni < 2; ++ni) bfr[ni] = *(const bf16x8*)(bs + ((wn * 64 + ni * 32 + r) * 72 + ks * 16 + 8 * h) * 2);
; #pragma unroll
;       for (int mi = 0; mi < 2; ++mi)
; #pragma unroll
;         for (int ni = 0; ni < 2; ++ni) {
;           if (SWAP) acc[mi][ni] = MFMA32(bfr[ni], af[mi], acc[mi][ni]);
;           else acc[mi][ni] = MFMA32(af[mi], bfr[ni], acc[mi][ni]);
;         }
;     }
;   };
;   gload(0, ra0, rb0);
;   lstore(0, ra0, rb0);
;   gload(1, ra1, rb1);
;   __syncthreads();
;   for (int kt = 0; kt < nk; kt += 2) {
;     if (kt + 2 < nk) gload(kt + 2, ra0, rb0);
;     compute(0);
;     lstore(1, ra1, rb1);
;     __syncthreads();
;     if (kt + 3 < nk) gload(kt + 3, ra1, rb1);
;     compute(1);
;     if (kt + 2 < nk) lstore(0, ra0, rb0);
;     __syncthreads();
	ds_read_b128 v[132:135], v210 offset:32768
	ds_read_b128 v[136:139], v210 offset:36864
	ds_read_b128 v[140:143], v214 offset:32768
	ds_read_b128 v[144:147], v214 offset:36864
	ds_read_b128 v[148:151], v214 offset:49152
	ds_read_b128 v[158:161], v214 offset:53248
	s_mov_b32 m0, s44
	s_nop 0
	global_load_lds_dwordx4 v208, s[68:69]
	global_load_lds_dwordx4 v209, s[70:71] offset:1024
	global_load_lds_dwordx4 v208, s[72:73] offset:2048
	global_load_lds_dwordx4 v209, s[74:75] offset:3072
	ds_read_b128 v[162:165], v211 offset:32768
	ds_read_b128 v[168:171], v211 offset:36864
	ds_read_b128 v[172:175], v215 offset:32768
	ds_read_b128 v[176:179], v215 offset:36864
	ds_read_b128 v[180:183], v215 offset:49152
	ds_read_b128 v[184:187], v215 offset:53248
	s_waitcnt lgkmcnt(6)
	v_mfma_f32_32x32x16_bf16 v[4:19], v[140:143], v[132:135], v[4:19]
	v_mfma_f32_32x32x16_bf16 v[68:83], v[140:143], v[136:139], v[68:83]
	v_mfma_f32_32x32x16_bf16 v[20:35], v[144:147], v[132:135], v[20:35]
	v_mfma_f32_32x32x16_bf16 v[84:99], v[144:147], v[136:139], v[84:99]
	v_mfma_f32_32x32x16_bf16 v[36:51], v[148:151], v[132:135], v[36:51]
	v_mfma_f32_32x32x16_bf16 v[100:115], v[148:151], v[136:139], v[100:115]
	v_mfma_f32_32x32x16_bf16 v[52:67], v[158:161], v[132:135], v[52:67]
	v_mfma_f32_32x32x16_bf16 v[116:131], v[158:161], v[136:139], v[116:131]
	s_mov_b32 m0, s46
	s_nop 0
	global_load_lds_dwordx4 v208, s[76:77]
	global_load_lds_dwordx4 v209, s[78:79] offset:1024
	global_load_lds_dwordx4 v208, s[80:81] offset:2048
	global_load_lds_dwordx4 v209, s[82:83] offset:3072
	v_add_u32_e32 v208, 0x80, v208
	v_add_u32_e32 v209, 0x80, v209
	ds_read_b128 v[132:135], v212 offset:32768
	ds_read_b128 v[136:139], v212 offset:36864
	ds_read_b128 v[140:143], v216 offset:32768
	ds_read_b128 v[144:147], v216 offset:36864
	ds_read_b128 v[148:151], v216 offset:49152
	ds_read_b128 v[158:161], v216 offset:53248
	s_waitcnt lgkmcnt(6)
	v_mfma_f32_32x32x16_bf16 v[4:19], v[172:175], v[162:165], v[4:19]
	v_mfma_f32_32x32x16_bf16 v[68:83], v[172:175], v[168:171], v[68:83]
	v_mfma_f32_32x32x16_bf16 v[20:35], v[176:179], v[162:165], v[20:35]
	v_mfma_f32_32x32x16_bf16 v[84:99], v[176:179], v[168:171], v[84:99]
	v_mfma_f32_32x32x16_bf16 v[36:51], v[180:183], v[162:165], v[36:51]
	v_mfma_f32_32x32x16_bf16 v[100:115], v[180:183], v[168:171], v[100:115]
	v_mfma_f32_32x32x16_bf16 v[52:67], v[184:187], v[162:165], v[52:67]
	v_mfma_f32_32x32x16_bf16 v[116:131], v[184:187], v[168:171], v[116:131]
	ds_read_b128 v[162:165], v213 offset:32768
	ds_read_b128 v[168:171], v213 offset:36864
	ds_read_b128 v[172:175], v217 offset:32768
	ds_read_b128 v[176:179], v217 offset:36864
	ds_read_b128 v[180:183], v217 offset:49152
	ds_read_b128 v[184:187], v217 offset:53248
	s_waitcnt lgkmcnt(6)
	v_mfma_f32_32x32x16_bf16 v[4:19], v[140:143], v[132:135], v[4:19]
	v_mfma_f32_32x32x16_bf16 v[68:83], v[140:143], v[136:139], v[68:83]
	v_mfma_f32_32x32x16_bf16 v[20:35], v[144:147], v[132:135], v[20:35]
	v_mfma_f32_32x32x16_bf16 v[84:99], v[144:147], v[136:139], v[84:99]
	v_mfma_f32_32x32x16_bf16 v[36:51], v[148:151], v[132:135], v[36:51]
	v_mfma_f32_32x32x16_bf16 v[100:115], v[148:151], v[136:139], v[100:115]
	v_mfma_f32_32x32x16_bf16 v[52:67], v[158:161], v[132:135], v[52:67]
	v_mfma_f32_32x32x16_bf16 v[116:131], v[158:161], v[136:139], v[116:131]
	s_waitcnt lgkmcnt(0)
	v_mfma_f32_32x32x16_bf16 v[4:19], v[172:175], v[162:165], v[4:19]
	v_mfma_f32_32x32x16_bf16 v[68:83], v[172:175], v[168:171], v[68:83]
	v_mfma_f32_32x32x16_bf16 v[20:35], v[176:179], v[162:165], v[20:35]
	v_mfma_f32_32x32x16_bf16 v[84:99], v[176:179], v[168:171], v[84:99]
	v_mfma_f32_32x32x16_bf16 v[36:51], v[180:183], v[162:165], v[36:51]
	v_mfma_f32_32x32x16_bf16 v[100:115], v[180:183], v[168:171], v[100:115]
	v_mfma_f32_32x32x16_bf16 v[52:67], v[184:187], v[162:165], v[52:67]
	v_mfma_f32_32x32x16_bf16 v[116:131], v[184:187], v[168:171], v[116:131]
	s_waitcnt vmcnt(0) lgkmcnt(0)
	s_barrier
	ds_read_b128 v[132:135], v210 offset:0
	ds_read_b128 v[136:139], v210 offset:4096
	ds_read_b128 v[140:143], v214 offset:0
	ds_read_b128 v[144:147], v214 offset:4096
	ds_read_b128 v[148:151], v214 offset:16384
	ds_read_b128 v[158:161], v214 offset:20480
	s_mov_b32 m0, s45
	s_nop 0
	global_load_lds_dwordx4 v208, s[68:69]
	global_load_lds_dwordx4 v209, s[70:71] offset:1024
	global_load_lds_dwordx4 v208, s[72:73] offset:2048
	global_load_lds_dwordx4 v209, s[74:75] offset:3072
	ds_read_b128 v[162:165], v211 offset:0
	ds_read_b128 v[168:171], v211 offset:4096
	ds_read_b128 v[172:175], v215 offset:0
	ds_read_b128 v[176:179], v215 offset:4096
	ds_read_b128 v[180:183], v215 offset:16384
	ds_read_b128 v[184:187], v215 offset:20480
	s_waitcnt lgkmcnt(6)
	v_mfma_f32_32x32x16_bf16 v[4:19], v[140:143], v[132:135], v[4:19]
	v_mfma_f32_32x32x16_bf16 v[68:83], v[140:143], v[136:139], v[68:83]
	v_mfma_f32_32x32x16_bf16 v[20:35], v[144:147], v[132:135], v[20:35]
	v_mfma_f32_32x32x16_bf16 v[84:99], v[144:147], v[136:139], v[84:99]
	v_mfma_f32_32x32x16_bf16 v[36:51], v[148:151], v[132:135], v[36:51]
	v_mfma_f32_32x32x16_bf16 v[100:115], v[148:151], v[136:139], v[100:115]
	v_mfma_f32_32x32x16_bf16 v[52:67], v[158:161], v[132:135], v[52:67]
	v_mfma_f32_32x32x16_bf16 v[116:131], v[158:161], v[136:139], v[116:131]
	s_mov_b32 m0, s47
	s_nop 0
	global_load_lds_dwordx4 v208, s[76:77]
	global_load_lds_dwordx4 v209, s[78:79] offset:1024
	global_load_lds_dwordx4 v208, s[80:81] offset:2048
	global_load_lds_dwordx4 v209, s[82:83] offset:3072
	v_add_u32_e32 v208, 0x80, v208
	v_add_u32_e32 v209, 0x80, v209
	ds_read_b128 v[132:135], v212 offset:0
	ds_read_b128 v[136:139], v212 offset:4096
	ds_read_b128 v[140:143], v216 offset:0
	ds_read_b128 v[144:147], v216 offset:4096
	ds_read_b128 v[148:151], v216 offset:16384
	ds_read_b128 v[158:161], v216 offset:20480
	s_waitcnt lgkmcnt(6)
; #define MFMA32(a, b, c) __builtin_amdgcn_mfma_f32_32x32x16_bf16((a), (b), (c), 0, 0, 0)
; template <bool SWAP, class Epi>
; DI void gemm_tile(const u16* __restrict__ A, int lda, const u16* __restrict__ Bw, int ldb, int K, char* lds, Epi epi) {
;     ...
;   auto compute = [&](int st) {
;     const char* as = lds + st * GEMM_STAGE;
;     const char* bs = as + 36864;
; #pragma unroll
;     for (int ks = 0; ks < 4; ++ks) {
;       bf16x8 af[2], bfr[2];
; #pragma unroll
;       for (int mi = 0; mi < 2; ++mi) af[mi] = *(const bf16x8*)(as + ((wm * 64 + mi * 32 + r) * 72 + ks * 16 + 8 * h) * 2);
; #pragma unroll
;       for (int ni = 0; ni < 2; ++ni) bfr[ni] = *(const bf16x8*)(bs + ((wn * 64 + ni * 32 + r) * 72 + ks * 16 + 8 * h) * 2);
; #pragma unroll
;       for (int mi = 0; mi < 2; ++mi)
; #pragma unroll
;         for (int ni = 0; ni < 2; ++ni) {
;           if (SWAP) acc[mi][ni] = MFMA32(bfr[ni], af[mi], acc[mi][ni]);
;           else acc[mi][ni] = MFMA32(af[mi], bfr[ni], acc[mi][ni]);
;         }
;     }
;   };
;   gload(0, ra0, rb0);
;   lstore(0, ra0, rb0);
;   gload(1, ra1, rb1);
;   __syncthreads();
;   for (int kt = 0; kt < nk; kt += 2) {
;     if (kt + 2 < nk) gload(kt + 2, ra0, rb0);
;     compute(0);
;     lstore(1, ra1, rb1);
;     __syncthreads();
;     if (kt + 3 < nk) gload(kt + 3, ra1, rb1);
;     compute(1);
;     if (kt + 2 < nk) lstore(0, ra0, rb0);
;     __syncthreads();
	v_mfma_f32_32x32x16_bf16 v[4:19], v[172:175], v[162:165], v[4:19]
	v_mfma_f32_32x32x16_bf16 v[68:83], v[172:175], v[168:171], v[68:83]
	v_mfma_f32_32x32x16_bf16 v[20:35], v[176:179], v[162:165], v[20:35]
	v_mfma_f32_32x32x16_bf16 v[84:99], v[176:179], v[168:171], v[84:99]
	v_mfma_f32_32x32x16_bf16 v[36:51], v[180:183], v[162:165], v[36:51]
	v_mfma_f32_32x32x16_bf16 v[100:115], v[180:183], v[168:171], v[100:115]
	v_mfma_f32_32x32x16_bf16 v[52:67], v[184:187], v[162:165], v[52:67]
	v_mfma_f32_32x32x16_bf16 v[116:131], v[184:187], v[168:171], v[116:131]
	ds_read_b128 v[162:165], v213 offset:0
	ds_read_b128 v[168:171], v213 offset:4096
	ds_read_b128 v[172:175], v217 offset:0
	ds_read_b128 v[176:179], v217 offset:4096
	ds_read_b128 v[180:183], v217 offset:16384
	ds_read_b128 v[184:187], v217 offset:20480
	s_waitcnt lgkmcnt(6)
	v_mfma_f32_32x32x16_bf16 v[4:19], v[140:143], v[132:135], v[4:19]
	v_mfma_f32_32x32x16_bf16 v[68:83], v[140:143], v[136:139], v[68:83]
	v_mfma_f32_32x32x16_bf16 v[20:35], v[144:147], v[132:135], v[20:35]
	v_mfma_f32_32x32x16_bf16 v[84:99], v[144:147], v[136:139], v[84:99]
	v_mfma_f32_32x32x16_bf16 v[36:51], v[148:151], v[132:135], v[36:51]
	v_mfma_f32_32x32x16_bf16 v[100:115], v[148:151], v[136:139], v[100:115]
	v_mfma_f32_32x32x16_bf16 v[52:67], v[158:161], v[132:135], v[52:67]
	v_mfma_f32_32x32x16_bf16 v[116:131], v[158:161], v[136:139], v[116:131]
	s_waitcnt lgkmcnt(0)
	v_mfma_f32_32x32x16_bf16 v[4:19], v[172:175], v[162:165], v[4:19]
	v_mfma_f32_32x32x16_bf16 v[68:83], v[172:175], v[168:171], v[68:83]
	v_mfma_f32_32x32x16_bf16 v[20:35], v[176:179], v[162:165], v[20:35]
	v_mfma_f32_32x32x16_bf16 v[84:99], v[176:179], v[168:171], v[84:99]
	v_mfma_f32_32x32x16_bf16 v[36:51], v[180:183], v[162:165], v[36:51]
	v_mfma_f32_32x32x16_bf16 v[100:115], v[180:183], v[168:171], v[100:115]
	v_mfma_f32_32x32x16_bf16 v[52:67], v[184:187], v[162:165], v[52:67]
	v_mfma_f32_32x32x16_bf16 v[116:131], v[184:187], v[168:171], v[116:131]
	s_waitcnt vmcnt(0) lgkmcnt(0)
	s_barrier
	ds_read_b128 v[132:135], v210 offset:32768
	ds_read_b128 v[136:139], v210 offset:36864
	ds_read_b128 v[140:143], v214 offset:32768
	ds_read_b128 v[144:147], v214 offset:36864
	ds_read_b128 v[148:151], v214 offset:49152
	ds_read_b128 v[158:161], v214 offset:53248
	s_mov_b32 m0, s44
	s_nop 0
	global_load_lds_dwordx4 v208, s[68:69]
	global_load_lds_dwordx4 v209, s[70:71] offset:1024
	global_load_lds_dwordx4 v208, s[72:73] offset:2048
	global_load_lds_dwordx4 v209, s[74:75] offset:3072
	ds_read_b128 v[162:165], v211 offset:32768
	ds_read_b128 v[168:171], v211 offset:36864
	ds_read_b128 v[172:175], v215 offset:32768
	ds_read_b128 v[176:179], v215 offset:36864
	ds_read_b128 v[180:183], v215 offset:49152
	ds_read_b128 v[184:187], v215 offset:53248
	s_waitcnt lgkmcnt(6)
	v_mfma_f32_32x32x16_bf16 v[4:19], v[140:143], v[132:135], v[4:19]
	v_mfma_f32_32x32x16_bf16 v[68:83], v[140:143], v[136:139], v[68:83]
	v_mfma_f32_32x32x16_bf16 v[20:35], v[144:147], v[132:135], v[20:35]
	v_mfma_f32_32x32x16_bf16 v[84:99], v[144:147], v[136:139], v[84:99]
	v_mfma_f32_32x32x16_bf16 v[36:51], v[148:151], v[132:135], v[36:51]
	v_mfma_f32_32x32x16_bf16 v[100:115], v[148:151], v[136:139], v[100:115]
	v_mfma_f32_32x32x16_bf16 v[52:67], v[158:161], v[132:135], v[52:67]
	v_mfma_f32_32x32x16_bf16 v[116:131], v[158:161], v[136:139], v[116:131]
	s_mov_b32 m0, s46
	s_nop 0
	global_load_lds_dwordx4 v208, s[76:77]
	global_load_lds_dwordx4 v209, s[78:79] offset:1024
	global_load_lds_dwordx4 v208, s[80:81] offset:2048
	global_load_lds_dwordx4 v209, s[82:83] offset:3072
	v_add_u32_e32 v208, 0x80, v208
	v_add_u32_e32 v209, 0x80, v209
	ds_read_b128 v[132:135], v212 offset:32768
	ds_read_b128 v[136:139], v212 offset:36864
	ds_read_b128 v[140:143], v216 offset:32768
	ds_read_b128 v[144:147], v216 offset:36864
	ds_read_b128 v[148:151], v216 offset:49152
	ds_read_b128 v[158:161], v216 offset:53248
	s_waitcnt lgkmcnt(6)
	v_mfma_f32_32x32x16_bf16 v[4:19], v[172:175], v[162:165], v[4:19]
	v_mfma_f32_32x32x16_bf16 v[68:83], v[172:175], v[168:171], v[68:83]
	v_mfma_f32_32x32x16_bf16 v[20:35], v[176:179], v[162:165], v[20:35]
	v_mfma_f32_32x32x16_bf16 v[84:99], v[176:179], v[168:171], v[84:99]
	v_mfma_f32_32x32x16_bf16 v[36:51], v[180:183], v[162:165], v[36:51]
	v_mfma_f32_32x32x16_bf16 v[100:115], v[180:183], v[168:171], v[100:115]
	v_mfma_f32_32x32x16_bf16 v[52:67], v[184:187], v[162:165], v[52:67]
	v_mfma_f32_32x32x16_bf16 v[116:131], v[184:187], v[168:171], v[116:131]
	ds_read_b128 v[162:165], v213 offset:32768
	ds_read_b128 v[168:171], v213 offset:36864
	ds_read_b128 v[172:175], v217 offset:32768
	ds_read_b128 v[176:179], v217 offset:36864
	ds_read_b128 v[180:183], v217 offset:49152
	ds_read_b128 v[184:187], v217 offset:53248
	s_waitcnt lgkmcnt(6)
	v_mfma_f32_32x32x16_bf16 v[4:19], v[140:143], v[132:135], v[4:19]
	v_mfma_f32_32x32x16_bf16 v[68:83], v[140:143], v[136:139], v[68:83]
	v_mfma_f32_32x32x16_bf16 v[20:35], v[144:147], v[132:135], v[20:35]
	v_mfma_f32_32x32x16_bf16 v[84:99], v[144:147], v[136:139], v[84:99]
	v_mfma_f32_32x32x16_bf16 v[36:51], v[148:151], v[132:135], v[36:51]
	v_mfma_f32_32x32x16_bf16 v[100:115], v[148:151], v[136:139], v[100:115]
	v_mfma_f32_32x32x16_bf16 v[52:67], v[158:161], v[132:135], v[52:67]
	v_mfma_f32_32x32x16_bf16 v[116:131], v[158:161], v[136:139], v[116:131]
	s_waitcnt lgkmcnt(0)
	v_mfma_f32_32x32x16_bf16 v[4:19], v[172:175], v[162:165], v[4:19]
	v_mfma_f32_32x32x16_bf16 v[68:83], v[172:175], v[168:171], v[68:83]
	v_mfma_f32_32x32x16_bf16 v[20:35], v[176:179], v[162:165], v[20:35]
	v_mfma_f32_32x32x16_bf16 v[84:99], v[176:179], v[168:171], v[84:99]
	v_mfma_f32_32x32x16_bf16 v[36:51], v[180:183], v[162:165], v[36:51]
	v_mfma_f32_32x32x16_bf16 v[100:115], v[180:183], v[168:171], v[100:115]
	v_mfma_f32_32x32x16_bf16 v[52:67], v[184:187], v[162:165], v[52:67]
	v_mfma_f32_32x32x16_bf16 v[116:131], v[184:187], v[168:171], v[116:131]
	s_waitcnt vmcnt(0) lgkmcnt(0)
	s_barrier
; #define MFMA32(a, b, c) __builtin_amdgcn_mfma_f32_32x32x16_bf16((a), (b), (c), 0, 0, 0)
; template <bool SWAP, class Epi>
; DI void gemm_tile(const u16* __restrict__ A, int lda, const u16* __restrict__ Bw, int ldb, int K, char* lds, Epi epi) {
;     ...
;   auto compute = [&](int st) {
;     const char* as = lds + st * GEMM_STAGE;
;     const char* bs = as + 36864;
; #pragma unroll
;     for (int ks = 0; ks < 4; ++ks) {
;       bf16x8 af[2], bfr[2];
; #pragma unroll
;       for (int mi = 0; mi < 2; ++mi) af[mi] = *(const bf16x8*)(as + ((wm * 64 + mi * 32 + r) * 72 + ks * 16 + 8 * h) * 2);
; #pragma unroll
;       for (int ni = 0; ni < 2; ++ni) bfr[ni] = *(const bf16x8*)(bs + ((wn * 64 + ni * 32 + r) * 72 + ks * 16 + 8 * h) * 2);
; #pragma unroll
;       for (int mi = 0; mi < 2; ++mi)
; #pragma unroll
;         for (int ni = 0; ni < 2; ++ni) {
;           if (SWAP) acc[mi][ni] = MFMA32(bfr[ni], af[mi], acc[mi][ni]);
;           else acc[mi][ni] = MFMA32(af[mi], bfr[ni], acc[mi][ni]);
;         }
;     }
;   };
;   gload(0, ra0, rb0);
;   lstore(0, ra0, rb0);
;   gload(1, ra1, rb1);
;   __syncthreads();
;   for (int kt = 0; kt < nk; kt += 2) {
;     if (kt + 2 < nk) gload(kt + 2, ra0, rb0);
;     compute(0);
;     lstore(1, ra1, rb1);
;     __syncthreads();
;     if (kt + 3 < nk) gload(kt + 3, ra1, rb1);
;     compute(1);
;     if (kt + 2 < nk) lstore(0, ra0, rb0);
;     __syncthreads();
	ds_read_b128 v[132:135], v210 offset:0
	ds_read_b128 v[136:139], v210 offset:4096
	ds_read_b128 v[140:143], v214 offset:0
	ds_read_b128 v[144:147], v214 offset:4096
	ds_read_b128 v[148:151], v214 offset:16384
	ds_read_b128 v[158:161], v214 offset:20480
	s_mov_b32 m0, s45
	s_nop 0
	global_load_lds_dwordx4 v208, s[68:69]
	global_load_lds_dwordx4 v209, s[70:71] offset:1024
	global_load_lds_dwordx4 v208, s[72:73] offset:2048
	global_load_lds_dwordx4 v209, s[74:75] offset:3072
	ds_read_b128 v[162:165], v211 offset:0
	ds_read_b128 v[168:171], v211 offset:4096
	ds_read_b128 v[172:175], v215 offset:0
	ds_read_b128 v[176:179], v215 offset:4096
	ds_read_b128 v[180:183], v215 offset:16384
	ds_read_b128 v[184:187], v215 offset:20480
	s_waitcnt lgkmcnt(6)
	v_mfma_f32_32x32x16_bf16 v[4:19], v[140:143], v[132:135], v[4:19]
	v_mfma_f32_32x32x16_bf16 v[68:83], v[140:143], v[136:139], v[68:83]
	v_mfma_f32_32x32x16_bf16 v[20:35], v[144:147], v[132:135], v[20:35]
	v_mfma_f32_32x32x16_bf16 v[84:99], v[144:147], v[136:139], v[84:99]
	v_mfma_f32_32x32x16_bf16 v[36:51], v[148:151], v[132:135], v[36:51]
	v_mfma_f32_32x32x16_bf16 v[100:115], v[148:151], v[136:139], v[100:115]
	v_mfma_f32_32x32x16_bf16 v[52:67], v[158:161], v[132:135], v[52:67]
	v_mfma_f32_32x32x16_bf16 v[116:131], v[158:161], v[136:139], v[116:131]
	s_mov_b32 m0, s47
	s_nop 0
	global_load_lds_dwordx4 v208, s[76:77]
	global_load_lds_dwordx4 v209, s[78:79] offset:1024
	global_load_lds_dwordx4 v208, s[80:81] offset:2048
	global_load_lds_dwordx4 v209, s[82:83] offset:3072
	v_add_u32_e32 v208, 0x80, v208
	v_add_u32_e32 v209, 0x80, v209
	ds_read_b128 v[132:135], v212 offset:0
	ds_read_b128 v[136:139], v212 offset:4096
	ds_read_b128 v[140:143], v216 offset:0
	ds_read_b128 v[144:147], v216 offset:4096
	ds_read_b128 v[148:151], v216 offset:16384
	ds_read_b128 v[158:161], v216 offset:20480
	s_waitcnt lgkmcnt(6)
	v_mfma_f32_32x32x16_bf16 v[4:19], v[172:175], v[162:165], v[4:19]
	v_mfma_f32_32x32x16_bf16 v[68:83], v[172:175], v[168:171], v[68:83]
	v_mfma_f32_32x32x16_bf16 v[20:35], v[176:179], v[162:165], v[20:35]
	v_mfma_f32_32x32x16_bf16 v[84:99], v[176:179], v[168:171], v[84:99]
	v_mfma_f32_32x32x16_bf16 v[36:51], v[180:183], v[162:165], v[36:51]
	v_mfma_f32_32x32x16_bf16 v[100:115], v[180:183], v[168:171], v[100:115]
	v_mfma_f32_32x32x16_bf16 v[52:67], v[184:187], v[162:165], v[52:67]
	v_mfma_f32_32x32x16_bf16 v[116:131], v[184:187], v[168:171], v[116:131]
	ds_read_b128 v[162:165], v213 offset:0
	ds_read_b128 v[168:171], v213 offset:4096
	ds_read_b128 v[172:175], v217 offset:0
	ds_read_b128 v[176:179], v217 offset:4096
	ds_read_b128 v[180:183], v217 offset:16384
	ds_read_b128 v[184:187], v217 offset:20480
	s_waitcnt lgkmcnt(6)
	v_mfma_f32_32x32x16_bf16 v[4:19], v[140:143], v[132:135], v[4:19]
	v_mfma_f32_32x32x16_bf16 v[68:83], v[140:143], v[136:139], v[68:83]
	v_mfma_f32_32x32x16_bf16 v[20:35], v[144:147], v[132:135], v[20:35]
	v_mfma_f32_32x32x16_bf16 v[84:99], v[144:147], v[136:139], v[84:99]
	v_mfma_f32_32x32x16_bf16 v[36:51], v[148:151], v[132:135], v[36:51]
	v_mfma_f32_32x32x16_bf16 v[100:115], v[148:151], v[136:139], v[100:115]
	v_mfma_f32_32x32x16_bf16 v[52:67], v[158:161], v[132:135], v[52:67]
	v_mfma_f32_32x32x16_bf16 v[116:131], v[158:161], v[136:139], v[116:131]
	s_waitcnt lgkmcnt(0)
	v_mfma_f32_32x32x16_bf16 v[4:19], v[172:175], v[162:165], v[4:19]
	v_mfma_f32_32x32x16_bf16 v[68:83], v[172:175], v[168:171], v[68:83]
	v_mfma_f32_32x32x16_bf16 v[20:35], v[176:179], v[162:165], v[20:35]
	v_mfma_f32_32x32x16_bf16 v[84:99], v[176:179], v[168:171], v[84:99]
	v_mfma_f32_32x32x16_bf16 v[36:51], v[180:183], v[162:165], v[36:51]
	v_mfma_f32_32x32x16_bf16 v[100:115], v[180:183], v[168:171], v[100:115]
	v_mfma_f32_32x32x16_bf16 v[52:67], v[184:187], v[162:165], v[52:67]
	v_mfma_f32_32x32x16_bf16 v[116:131], v[184:187], v[168:171], v[116:131]
	s_waitcnt vmcnt(0) lgkmcnt(0)
	s_barrier
	ds_read_b128 v[132:135], v210 offset:32768
	ds_read_b128 v[136:139], v210 offset:36864
	ds_read_b128 v[140:143], v214 offset:32768
	ds_read_b128 v[144:147], v214 offset:36864
	ds_read_b128 v[148:151], v214 offset:49152
	ds_read_b128 v[158:161], v214 offset:53248
	s_mov_b32 m0, s44
	s_nop 0
	global_load_lds_dwordx4 v208, s[68:69]
	global_load_lds_dwordx4 v209, s[70:71] offset:1024
	global_load_lds_dwordx4 v208, s[72:73] offset:2048
	global_load_lds_dwordx4 v209, s[74:75] offset:3072
	ds_read_b128 v[162:165], v211 offset:32768
	ds_read_b128 v[168:171], v211 offset:36864
	ds_read_b128 v[172:175], v215 offset:32768
	ds_read_b128 v[176:179], v215 offset:36864
	ds_read_b128 v[180:183], v215 offset:49152
	ds_read_b128 v[184:187], v215 offset:53248
	s_waitcnt lgkmcnt(6)
	v_mfma_f32_32x32x16_bf16 v[4:19], v[140:143], v[132:135], v[4:19]
	v_mfma_f32_32x32x16_bf16 v[68:83], v[140:143], v[136:139], v[68:83]
	v_mfma_f32_32x32x16_bf16 v[20:35], v[144:147], v[132:135], v[20:35]
	v_mfma_f32_32x32x16_bf16 v[84:99], v[144:147], v[136:139], v[84:99]
	v_mfma_f32_32x32x16_bf16 v[36:51], v[148:151], v[132:135], v[36:51]
	v_mfma_f32_32x32x16_bf16 v[100:115], v[148:151], v[136:139], v[100:115]
	v_mfma_f32_32x32x16_bf16 v[52:67], v[158:161], v[132:135], v[52:67]
	v_mfma_f32_32x32x16_bf16 v[116:131], v[158:161], v[136:139], v[116:131]
	s_mov_b32 m0, s46
	s_nop 0
	global_load_lds_dwordx4 v208, s[76:77]
	global_load_lds_dwordx4 v209, s[78:79] offset:1024
	global_load_lds_dwordx4 v208, s[80:81] offset:2048
	global_load_lds_dwordx4 v209, s[82:83] offset:3072
	v_add_u32_e32 v208, 0x80, v208
	v_add_u32_e32 v209, 0x80, v209
	ds_read_b128 v[132:135], v212 offset:32768
	ds_read_b128 v[136:139], v212 offset:36864
	ds_read_b128 v[140:143], v216 offset:32768
	ds_read_b128 v[144:147], v216 offset:36864
	ds_read_b128 v[148:151], v216 offset:49152
	ds_read_b128 v[158:161], v216 offset:53248
	s_waitcnt lgkmcnt(6)
; #define MFMA32(a, b, c) __builtin_amdgcn_mfma_f32_32x32x16_bf16((a), (b), (c), 0, 0, 0)
; template <bool SWAP, class Epi>
; DI void gemm_tile(const u16* __restrict__ A, int lda, const u16* __restrict__ Bw, int ldb, int K, char* lds, Epi epi) {
;     ...
;   auto compute = [&](int st) {
;     const char* as = lds + st * GEMM_STAGE;
;     const char* bs = as + 36864;
; #pragma unroll
;     for (int ks = 0; ks < 4; ++ks) {
;       bf16x8 af[2], bfr[2];
; #pragma unroll
;       for (int mi = 0; mi < 2; ++mi) af[mi] = *(const bf16x8*)(as + ((wm * 64 + mi * 32 + r) * 72 + ks * 16 + 8 * h) * 2);
; #pragma unroll
;       for (int ni = 0; ni < 2; ++ni) bfr[ni] = *(const bf16x8*)(bs + ((wn * 64 + ni * 32 + r) * 72 + ks * 16 + 8 * h) * 2);
; #pragma unroll
;       for (int mi = 0; mi < 2; ++mi)
; #pragma unroll
;         for (int ni = 0; ni < 2; ++ni) {
;           if (SWAP) acc[mi][ni] = MFMA32(bfr[ni], af[mi], acc[mi][ni]);
;           else acc[mi][ni] = MFMA32(af[mi], bfr[ni], acc[mi][ni]);
;         }
;     }
;   };
;   gload(0, ra0, rb0);
;   lstore(0, ra0, rb0);
;   gload(1, ra1, rb1);
;   __syncthreads();
;   for (int kt = 0; kt < nk; kt += 2) {
;     if (kt + 2 < nk) gload(kt + 2, ra0, rb0);
;     compute(0);
;     lstore(1, ra1, rb1);
;     __syncthreads();
;     if (kt + 3 < nk) gload(kt + 3, ra1, rb1);
;     compute(1);
;     if (kt + 2 < nk) lstore(0, ra0, rb0);
;     __syncthreads();
	v_mfma_f32_32x32x16_bf16 v[4:19], v[172:175], v[162:165], v[4:19]
	v_mfma_f32_32x32x16_bf16 v[68:83], v[172:175], v[168:171], v[68:83]
	v_mfma_f32_32x32x16_bf16 v[20:35], v[176:179], v[162:165], v[20:35]
	v_mfma_f32_32x32x16_bf16 v[84:99], v[176:179], v[168:171], v[84:99]
	v_mfma_f32_32x32x16_bf16 v[36:51], v[180:183], v[162:165], v[36:51]
	v_mfma_f32_32x32x16_bf16 v[100:115], v[180:183], v[168:171], v[100:115]
	v_mfma_f32_32x32x16_bf16 v[52:67], v[184:187], v[162:165], v[52:67]
	v_mfma_f32_32x32x16_bf16 v[116:131], v[184:187], v[168:171], v[116:131]
	ds_read_b128 v[162:165], v213 offset:32768
	ds_read_b128 v[168:171], v213 offset:36864
	ds_read_b128 v[172:175], v217 offset:32768
	ds_read_b128 v[176:179], v217 offset:36864
	ds_read_b128 v[180:183], v217 offset:49152
	ds_read_b128 v[184:187], v217 offset:53248
	s_waitcnt lgkmcnt(6)
	v_mfma_f32_32x32x16_bf16 v[4:19], v[140:143], v[132:135], v[4:19]
	v_mfma_f32_32x32x16_bf16 v[68:83], v[140:143], v[136:139], v[68:83]
	v_mfma_f32_32x32x16_bf16 v[20:35], v[144:147], v[132:135], v[20:35]
	v_mfma_f32_32x32x16_bf16 v[84:99], v[144:147], v[136:139], v[84:99]
	v_mfma_f32_32x32x16_bf16 v[36:51], v[148:151], v[132:135], v[36:51]
	v_mfma_f32_32x32x16_bf16 v[100:115], v[148:151], v[136:139], v[100:115]
	v_mfma_f32_32x32x16_bf16 v[52:67], v[158:161], v[132:135], v[52:67]
	v_mfma_f32_32x32x16_bf16 v[116:131], v[158:161], v[136:139], v[116:131]
	s_waitcnt lgkmcnt(0)
	v_mfma_f32_32x32x16_bf16 v[4:19], v[172:175], v[162:165], v[4:19]
	v_mfma_f32_32x32x16_bf16 v[68:83], v[172:175], v[168:171], v[68:83]
	v_mfma_f32_32x32x16_bf16 v[20:35], v[176:179], v[162:165], v[20:35]
	v_mfma_f32_32x32x16_bf16 v[84:99], v[176:179], v[168:171], v[84:99]
	v_mfma_f32_32x32x16_bf16 v[36:51], v[180:183], v[162:165], v[36:51]
	v_mfma_f32_32x32x16_bf16 v[100:115], v[180:183], v[168:171], v[100:115]
	v_mfma_f32_32x32x16_bf16 v[52:67], v[184:187], v[162:165], v[52:67]
	v_mfma_f32_32x32x16_bf16 v[116:131], v[184:187], v[168:171], v[116:131]
	s_waitcnt vmcnt(0) lgkmcnt(0)
	s_barrier
	ds_read_b128 v[132:135], v210 offset:0
	ds_read_b128 v[136:139], v210 offset:4096
	ds_read_b128 v[140:143], v214 offset:0
	ds_read_b128 v[144:147], v214 offset:4096
	ds_read_b128 v[148:151], v214 offset:16384
	ds_read_b128 v[158:161], v214 offset:20480
	s_mov_b32 m0, s45
	s_nop 0
	global_load_lds_dwordx4 v208, s[68:69]
	global_load_lds_dwordx4 v209, s[70:71] offset:1024
	global_load_lds_dwordx4 v208, s[72:73] offset:2048
	global_load_lds_dwordx4 v209, s[74:75] offset:3072
	ds_read_b128 v[162:165], v211 offset:0
	ds_read_b128 v[168:171], v211 offset:4096
	ds_read_b128 v[172:175], v215 offset:0
	ds_read_b128 v[176:179], v215 offset:4096
	ds_read_b128 v[180:183], v215 offset:16384
	ds_read_b128 v[184:187], v215 offset:20480
	s_waitcnt lgkmcnt(6)
	v_mfma_f32_32x32x16_bf16 v[4:19], v[140:143], v[132:135], v[4:19]
	v_mfma_f32_32x32x16_bf16 v[68:83], v[140:143], v[136:139], v[68:83]
	v_mfma_f32_32x32x16_bf16 v[20:35], v[144:147], v[132:135], v[20:35]
	v_mfma_f32_32x32x16_bf16 v[84:99], v[144:147], v[136:139], v[84:99]
	v_mfma_f32_32x32x16_bf16 v[36:51], v[148:151], v[132:135], v[36:51]
	v_mfma_f32_32x32x16_bf16 v[100:115], v[148:151], v[136:139], v[100:115]
	v_mfma_f32_32x32x16_bf16 v[52:67], v[158:161], v[132:135], v[52:67]
	v_mfma_f32_32x32x16_bf16 v[116:131], v[158:161], v[136:139], v[116:131]
	s_mov_b32 m0, s47
	s_nop 0
	global_load_lds_dwordx4 v208, s[76:77]
	global_load_lds_dwordx4 v209, s[78:79] offset:1024
	global_load_lds_dwordx4 v208, s[80:81] offset:2048
	global_load_lds_dwordx4 v209, s[82:83] offset:3072
	v_add_u32_e32 v208, 0x80, v208
	v_add_u32_e32 v209, 0x80, v209
	ds_read_b128 v[132:135], v212 offset:0
	ds_read_b128 v[136:139], v212 offset:4096
	ds_read_b128 v[140:143], v216 offset:0
	ds_read_b128 v[144:147], v216 offset:4096
	ds_read_b128 v[148:151], v216 offset:16384
	ds_read_b128 v[158:161], v216 offset:20480
	s_waitcnt lgkmcnt(6)
	v_mfma_f32_32x32x16_bf16 v[4:19], v[172:175], v[162:165], v[4:19]
	v_mfma_f32_32x32x16_bf16 v[68:83], v[172:175], v[168:171], v[68:83]
	v_mfma_f32_32x32x16_bf16 v[20:35], v[176:179], v[162:165], v[20:35]
	v_mfma_f32_32x32x16_bf16 v[84:99], v[176:179], v[168:171], v[84:99]
	v_mfma_f32_32x32x16_bf16 v[36:51], v[180:183], v[162:165], v[36:51]
	v_mfma_f32_32x32x16_bf16 v[100:115], v[180:183], v[168:171], v[100:115]
	v_mfma_f32_32x32x16_bf16 v[52:67], v[184:187], v[162:165], v[52:67]
	v_mfma_f32_32x32x16_bf16 v[116:131], v[184:187], v[168:171], v[116:131]
	ds_read_b128 v[162:165], v213 offset:0
	ds_read_b128 v[168:171], v213 offset:4096
	ds_read_b128 v[172:175], v217 offset:0
	ds_read_b128 v[176:179], v217 offset:4096
	ds_read_b128 v[180:183], v217 offset:16384
	ds_read_b128 v[184:187], v217 offset:20480
	s_waitcnt lgkmcnt(6)
	v_mfma_f32_32x32x16_bf16 v[4:19], v[140:143], v[132:135], v[4:19]
	v_mfma_f32_32x32x16_bf16 v[68:83], v[140:143], v[136:139], v[68:83]
	v_mfma_f32_32x32x16_bf16 v[20:35], v[144:147], v[132:135], v[20:35]
	v_mfma_f32_32x32x16_bf16 v[84:99], v[144:147], v[136:139], v[84:99]
	v_mfma_f32_32x32x16_bf16 v[36:51], v[148:151], v[132:135], v[36:51]
	v_mfma_f32_32x32x16_bf16 v[100:115], v[148:151], v[136:139], v[100:115]
	v_mfma_f32_32x32x16_bf16 v[52:67], v[158:161], v[132:135], v[52:67]
	v_mfma_f32_32x32x16_bf16 v[116:131], v[158:161], v[136:139], v[116:131]
	s_waitcnt lgkmcnt(0)
	v_mfma_f32_32x32x16_bf16 v[4:19], v[172:175], v[162:165], v[4:19]
	v_mfma_f32_32x32x16_bf16 v[68:83], v[172:175], v[168:171], v[68:83]
	v_mfma_f32_32x32x16_bf16 v[20:35], v[176:179], v[162:165], v[20:35]
	v_mfma_f32_32x32x16_bf16 v[84:99], v[176:179], v[168:171], v[84:99]
	v_mfma_f32_32x32x16_bf16 v[36:51], v[180:183], v[162:165], v[36:51]
	v_mfma_f32_32x32x16_bf16 v[100:115], v[180:183], v[168:171], v[100:115]
	v_mfma_f32_32x32x16_bf16 v[52:67], v[184:187], v[162:165], v[52:67]
	v_mfma_f32_32x32x16_bf16 v[116:131], v[184:187], v[168:171], v[116:131]
	s_waitcnt vmcnt(0) lgkmcnt(0)
	s_barrier
; #define MFMA32(a, b, c) __builtin_amdgcn_mfma_f32_32x32x16_bf16((a), (b), (c), 0, 0, 0)
; template <bool SWAP, class Epi>
; DI void gemm_tile(const u16* __restrict__ A, int lda, const u16* __restrict__ Bw, int ldb, int K, char* lds, Epi epi) {
;     ...
;   auto compute = [&](int st) {
;     const char* as = lds + st * GEMM_STAGE;
;     const char* bs = as + 36864;
; #pragma unroll
;     for (int ks = 0; ks < 4; ++ks) {
;       bf16x8 af[2], bfr[2];
; #pragma unroll
;       for (int mi = 0; mi < 2; ++mi) af[mi] = *(const bf16x8*)(as + ((wm * 64 + mi * 32 + r) * 72 + ks * 16 + 8 * h) * 2);
; #pragma unroll
;       for (int ni = 0; ni < 2; ++ni) bfr[ni] = *(const bf16x8*)(bs + ((wn * 64 + ni * 32 + r) * 72 + ks * 16 + 8 * h) * 2);
; #pragma unroll
;       for (int mi = 0; mi < 2; ++mi)
; #pragma unroll
;         for (int ni = 0; ni < 2; ++ni) {
;           if (SWAP) acc[mi][ni] = MFMA32(bfr[ni], af[mi], acc[mi][ni]);
;           else acc[mi][ni] = MFMA32(af[mi], bfr[ni], acc[mi][ni]);
;         }
;     }
;   };
;   gload(0, ra0, rb0);
;   lstore(0, ra0, rb0);
;   gload(1, ra1, rb1);
;   __syncthreads();
;   for (int kt = 0; kt < nk; kt += 2) {
;     if (kt + 2 < nk) gload(kt + 2, ra0, rb0);
;     compute(0);
;     lstore(1, ra1, rb1);
;     __syncthreads();
;     if (kt + 3 < nk) gload(kt + 3, ra1, rb1);
;     compute(1);
;     if (kt + 2 < nk) lstore(0, ra0, rb0);
;     __syncthreads();
	ds_read_b128 v[132:135], v210 offset:32768
	ds_read_b128 v[136:139], v210 offset:36864
	ds_read_b128 v[140:143], v214 offset:32768
	ds_read_b128 v[144:147], v214 offset:36864
	ds_read_b128 v[148:151], v214 offset:49152
	ds_read_b128 v[158:161], v214 offset:53248
	s_mov_b32 m0, s44
	s_nop 0
	global_load_lds_dwordx4 v208, s[68:69]
	global_load_lds_dwordx4 v209, s[70:71] offset:1024
	global_load_lds_dwordx4 v208, s[72:73] offset:2048
	global_load_lds_dwordx4 v209, s[74:75] offset:3072
	ds_read_b128 v[162:165], v211 offset:32768
	ds_read_b128 v[168:171], v211 offset:36864
	ds_read_b128 v[172:175], v215 offset:32768
	ds_read_b128 v[176:179], v215 offset:36864
	ds_read_b128 v[180:183], v215 offset:49152
	ds_read_b128 v[184:187], v215 offset:53248
	s_waitcnt lgkmcnt(6)
	v_mfma_f32_32x32x16_bf16 v[4:19], v[140:143], v[132:135], v[4:19]
	v_mfma_f32_32x32x16_bf16 v[68:83], v[140:143], v[136:139], v[68:83]
	v_mfma_f32_32x32x16_bf16 v[20:35], v[144:147], v[132:135], v[20:35]
	v_mfma_f32_32x32x16_bf16 v[84:99], v[144:147], v[136:139], v[84:99]
	v_mfma_f32_32x32x16_bf16 v[36:51], v[148:151], v[132:135], v[36:51]
	v_mfma_f32_32x32x16_bf16 v[100:115], v[148:151], v[136:139], v[100:115]
	v_mfma_f32_32x32x16_bf16 v[52:67], v[158:161], v[132:135], v[52:67]
	v_mfma_f32_32x32x16_bf16 v[116:131], v[158:161], v[136:139], v[116:131]
	s_mov_b32 m0, s46
	s_nop 0
	global_load_lds_dwordx4 v208, s[76:77]
	global_load_lds_dwordx4 v209, s[78:79] offset:1024
	global_load_lds_dwordx4 v208, s[80:81] offset:2048
	global_load_lds_dwordx4 v209, s[82:83] offset:3072
	v_add_u32_e32 v208, 0x80, v208
	v_add_u32_e32 v209, 0x80, v209
	ds_read_b128 v[132:135], v212 offset:32768
	ds_read_b128 v[136:139], v212 offset:36864
	ds_read_b128 v[140:143], v216 offset:32768
	ds_read_b128 v[144:147], v216 offset:36864
	ds_read_b128 v[148:151], v216 offset:49152
	ds_read_b128 v[158:161], v216 offset:53248
	s_waitcnt lgkmcnt(6)
	v_mfma_f32_32x32x16_bf16 v[4:19], v[172:175], v[162:165], v[4:19]
	v_mfma_f32_32x32x16_bf16 v[68:83], v[172:175], v[168:171], v[68:83]
	v_mfma_f32_32x32x16_bf16 v[20:35], v[176:179], v[162:165], v[20:35]
	v_mfma_f32_32x32x16_bf16 v[84:99], v[176:179], v[168:171], v[84:99]
	v_mfma_f32_32x32x16_bf16 v[36:51], v[180:183], v[162:165], v[36:51]
	v_mfma_f32_32x32x16_bf16 v[100:115], v[180:183], v[168:171], v[100:115]
	v_mfma_f32_32x32x16_bf16 v[52:67], v[184:187], v[162:165], v[52:67]
	v_mfma_f32_32x32x16_bf16 v[116:131], v[184:187], v[168:171], v[116:131]
	ds_read_b128 v[162:165], v213 offset:32768
	ds_read_b128 v[168:171], v213 offset:36864
	ds_read_b128 v[172:175], v217 offset:32768
	ds_read_b128 v[176:179], v217 offset:36864
	ds_read_b128 v[180:183], v217 offset:49152
	ds_read_b128 v[184:187], v217 offset:53248
	s_waitcnt lgkmcnt(6)
	v_mfma_f32_32x32x16_bf16 v[4:19], v[140:143], v[132:135], v[4:19]
	v_mfma_f32_32x32x16_bf16 v[68:83], v[140:143], v[136:139], v[68:83]
	v_mfma_f32_32x32x16_bf16 v[20:35], v[144:147], v[132:135], v[20:35]
	v_mfma_f32_32x32x16_bf16 v[84:99], v[144:147], v[136:139], v[84:99]
	v_mfma_f32_32x32x16_bf16 v[36:51], v[148:151], v[132:135], v[36:51]
	v_mfma_f32_32x32x16_bf16 v[100:115], v[148:151], v[136:139], v[100:115]
	v_mfma_f32_32x32x16_bf16 v[52:67], v[158:161], v[132:135], v[52:67]
	v_mfma_f32_32x32x16_bf16 v[116:131], v[158:161], v[136:139], v[116:131]
	s_waitcnt lgkmcnt(0)
	v_mfma_f32_32x32x16_bf16 v[4:19], v[172:175], v[162:165], v[4:19]
	v_mfma_f32_32x32x16_bf16 v[68:83], v[172:175], v[168:171], v[68:83]
	v_mfma_f32_32x32x16_bf16 v[20:35], v[176:179], v[162:165], v[20:35]
	v_mfma_f32_32x32x16_bf16 v[84:99], v[176:179], v[168:171], v[84:99]
	v_mfma_f32_32x32x16_bf16 v[36:51], v[180:183], v[162:165], v[36:51]
	v_mfma_f32_32x32x16_bf16 v[100:115], v[180:183], v[168:171], v[100:115]
	v_mfma_f32_32x32x16_bf16 v[52:67], v[184:187], v[162:165], v[52:67]
	v_mfma_f32_32x32x16_bf16 v[116:131], v[184:187], v[168:171], v[116:131]
	s_waitcnt vmcnt(0) lgkmcnt(0)
	s_barrier
	ds_read_b128 v[132:135], v210 offset:0
	ds_read_b128 v[136:139], v210 offset:4096
	ds_read_b128 v[140:143], v214 offset:0
	ds_read_b128 v[144:147], v214 offset:4096
	ds_read_b128 v[148:151], v214 offset:16384
	ds_read_b128 v[158:161], v214 offset:20480
	s_mov_b32 m0, s45
	s_nop 0
	global_load_lds_dwordx4 v208, s[68:69]
	global_load_lds_dwordx4 v209, s[70:71] offset:1024
	global_load_lds_dwordx4 v208, s[72:73] offset:2048
	global_load_lds_dwordx4 v209, s[74:75] offset:3072
	ds_read_b128 v[162:165], v211 offset:0
	ds_read_b128 v[168:171], v211 offset:4096
	ds_read_b128 v[172:175], v215 offset:0
	ds_read_b128 v[176:179], v215 offset:4096
	ds_read_b128 v[180:183], v215 offset:16384
	ds_read_b128 v[184:187], v215 offset:20480
	s_waitcnt lgkmcnt(6)
	v_mfma_f32_32x32x16_bf16 v[4:19], v[140:143], v[132:135], v[4:19]
	v_mfma_f32_32x32x16_bf16 v[68:83], v[140:143], v[136:139], v[68:83]
	v_mfma_f32_32x32x16_bf16 v[20:35], v[144:147], v[132:135], v[20:35]
	v_mfma_f32_32x32x16_bf16 v[84:99], v[144:147], v[136:139], v[84:99]
	v_mfma_f32_32x32x16_bf16 v[36:51], v[148:151], v[132:135], v[36:51]
	v_mfma_f32_32x32x16_bf16 v[100:115], v[148:151], v[136:139], v[100:115]
	v_mfma_f32_32x32x16_bf16 v[52:67], v[158:161], v[132:135], v[52:67]
	v_mfma_f32_32x32x16_bf16 v[116:131], v[158:161], v[136:139], v[116:131]
	s_mov_b32 m0, s47
	s_nop 0
	global_load_lds_dwordx4 v208, s[76:77]
	global_load_lds_dwordx4 v209, s[78:79] offset:1024
	global_load_lds_dwordx4 v208, s[80:81] offset:2048
	global_load_lds_dwordx4 v209, s[82:83] offset:3072
	v_add_u32_e32 v208, 0x80, v208
	v_add_u32_e32 v209, 0x80, v209
	ds_read_b128 v[132:135], v212 offset:0
	ds_read_b128 v[136:139], v212 offset:4096
	ds_read_b128 v[140:143], v216 offset:0
	ds_read_b128 v[144:147], v216 offset:4096
	ds_read_b128 v[148:151], v216 offset:16384
	ds_read_b128 v[158:161], v216 offset:20480
	s_waitcnt lgkmcnt(6)
; #define MFMA32(a, b, c) __builtin_amdgcn_mfma_f32_32x32x16_bf16((a), (b), (c), 0, 0, 0)
; template <bool SWAP, class Epi>
; DI void gemm_tile(const u16* __restrict__ A, int lda, const u16* __restrict__ Bw, int ldb, int K, char* lds, Epi epi) {
;     ...
;   auto compute = [&](int st) {
;     const char* as = lds + st * GEMM_STAGE;
;     const char* bs = as + 36864;
; #pragma unroll
;     for (int ks = 0; ks < 4; ++ks) {
;       bf16x8 af[2], bfr[2];
; #pragma unroll
;       for (int mi = 0; mi < 2; ++mi) af[mi] = *(const bf16x8*)(as + ((wm * 64 + mi * 32 + r) * 72 + ks * 16 + 8 * h) * 2);
; #pragma unroll
;       for (int ni = 0; ni < 2; ++ni) bfr[ni] = *(const bf16x8*)(bs + ((wn * 64 + ni * 32 + r) * 72 + ks * 16 + 8 * h) * 2);
; #pragma unroll
;       for (int mi = 0; mi < 2; ++mi)
; #pragma unroll
;         for (int ni = 0; ni < 2; ++ni) {
;           if (SWAP) acc[mi][ni] = MFMA32(bfr[ni], af[mi], acc[mi][ni]);
;           else acc[mi][ni] = MFMA32(af[mi], bfr[ni], acc[mi][ni]);
;         }
;     }
;   };
;   gload(0, ra0, rb0);
;   lstore(0, ra0, rb0);
;   gload(1, ra1, rb1);
;   __syncthreads();
;   for (int kt = 0; kt < nk; kt += 2) {
;     if (kt + 2 < nk) gload(kt + 2, ra0, rb0);
;     compute(0);
;     lstore(1, ra1, rb1);
;     __syncthreads();
;     if (kt + 3 < nk) gload(kt + 3, ra1, rb1);
;     compute(1);
;     if (kt + 2 < nk) lstore(0, ra0, rb0);
;     __syncthreads();
	v_mfma_f32_32x32x16_bf16 v[4:19], v[172:175], v[162:165], v[4:19]
	v_mfma_f32_32x32x16_bf16 v[68:83], v[172:175], v[168:171], v[68:83]
	v_mfma_f32_32x32x16_bf16 v[20:35], v[176:179], v[162:165], v[20:35]
	v_mfma_f32_32x32x16_bf16 v[84:99], v[176:179], v[168:171], v[84:99]
	v_mfma_f32_32x32x16_bf16 v[36:51], v[180:183], v[162:165], v[36:51]
	v_mfma_f32_32x32x16_bf16 v[100:115], v[180:183], v[168:171], v[100:115]
	v_mfma_f32_32x32x16_bf16 v[52:67], v[184:187], v[162:165], v[52:67]
	v_mfma_f32_32x32x16_bf16 v[116:131], v[184:187], v[168:171], v[116:131]
	ds_read_b128 v[162:165], v213 offset:0
	ds_read_b128 v[168:171], v213 offset:4096
	ds_read_b128 v[172:175], v217 offset:0
	ds_read_b128 v[176:179], v217 offset:4096
	ds_read_b128 v[180:183], v217 offset:16384
	ds_read_b128 v[184:187], v217 offset:20480
	s_waitcnt lgkmcnt(6)
	v_mfma_f32_32x32x16_bf16 v[4:19], v[140:143], v[132:135], v[4:19]
	v_mfma_f32_32x32x16_bf16 v[68:83], v[140:143], v[136:139], v[68:83]
	v_mfma_f32_32x32x16_bf16 v[20:35], v[144:147], v[132:135], v[20:35]
	v_mfma_f32_32x32x16_bf16 v[84:99], v[144:147], v[136:139], v[84:99]
	v_mfma_f32_32x32x16_bf16 v[36:51], v[148:151], v[132:135], v[36:51]
	v_mfma_f32_32x32x16_bf16 v[100:115], v[148:151], v[136:139], v[100:115]
	v_mfma_f32_32x32x16_bf16 v[52:67], v[158:161], v[132:135], v[52:67]
	v_mfma_f32_32x32x16_bf16 v[116:131], v[158:161], v[136:139], v[116:131]
	s_waitcnt lgkmcnt(0)
	v_mfma_f32_32x32x16_bf16 v[4:19], v[172:175], v[162:165], v[4:19]
	v_mfma_f32_32x32x16_bf16 v[68:83], v[172:175], v[168:171], v[68:83]
	v_mfma_f32_32x32x16_bf16 v[20:35], v[176:179], v[162:165], v[20:35]
	v_mfma_f32_32x32x16_bf16 v[84:99], v[176:179], v[168:171], v[84:99]
	v_mfma_f32_32x32x16_bf16 v[36:51], v[180:183], v[162:165], v[36:51]
	v_mfma_f32_32x32x16_bf16 v[100:115], v[180:183], v[168:171], v[100:115]
	v_mfma_f32_32x32x16_bf16 v[52:67], v[184:187], v[162:165], v[52:67]
	v_mfma_f32_32x32x16_bf16 v[116:131], v[184:187], v[168:171], v[116:131]
	s_waitcnt vmcnt(0) lgkmcnt(0)
	s_barrier
	ds_read_b128 v[132:135], v210 offset:32768
	ds_read_b128 v[136:139], v210 offset:36864
	ds_read_b128 v[140:143], v214 offset:32768
	ds_read_b128 v[144:147], v214 offset:36864
	ds_read_b128 v[148:151], v214 offset:49152
	ds_read_b128 v[158:161], v214 offset:53248
	s_mov_b32 m0, s44
	s_nop 0
	global_load_lds_dwordx4 v208, s[68:69]
	global_load_lds_dwordx4 v209, s[70:71] offset:1024
	global_load_lds_dwordx4 v208, s[72:73] offset:2048
	global_load_lds_dwordx4 v209, s[74:75] offset:3072
	ds_read_b128 v[162:165], v211 offset:32768
	ds_read_b128 v[168:171], v211 offset:36864
	ds_read_b128 v[172:175], v215 offset:32768
	ds_read_b128 v[176:179], v215 offset:36864
	ds_read_b128 v[180:183], v215 offset:49152
	ds_read_b128 v[184:187], v215 offset:53248
	s_waitcnt lgkmcnt(6)
	v_mfma_f32_32x32x16_bf16 v[4:19], v[140:143], v[132:135], v[4:19]
	v_mfma_f32_32x32x16_bf16 v[68:83], v[140:143], v[136:139], v[68:83]
	v_mfma_f32_32x32x16_bf16 v[20:35], v[144:147], v[132:135], v[20:35]
	v_mfma_f32_32x32x16_bf16 v[84:99], v[144:147], v[136:139], v[84:99]
	v_mfma_f32_32x32x16_bf16 v[36:51], v[148:151], v[132:135], v[36:51]
	v_mfma_f32_32x32x16_bf16 v[100:115], v[148:151], v[136:139], v[100:115]
	v_mfma_f32_32x32x16_bf16 v[52:67], v[158:161], v[132:135], v[52:67]
	v_mfma_f32_32x32x16_bf16 v[116:131], v[158:161], v[136:139], v[116:131]
	s_mov_b32 m0, s46
	s_nop 0
	global_load_lds_dwordx4 v208, s[76:77]
	global_load_lds_dwordx4 v209, s[78:79] offset:1024
	global_load_lds_dwordx4 v208, s[80:81] offset:2048
	global_load_lds_dwordx4 v209, s[82:83] offset:3072
	v_add_u32_e32 v208, 0x80, v208
	v_add_u32_e32 v209, 0x80, v209
	ds_read_b128 v[132:135], v212 offset:32768
	ds_read_b128 v[136:139], v212 offset:36864
	ds_read_b128 v[140:143], v216 offset:32768
	ds_read_b128 v[144:147], v216 offset:36864
	ds_read_b128 v[148:151], v216 offset:49152
	ds_read_b128 v[158:161], v216 offset:53248
	s_waitcnt lgkmcnt(6)
	v_mfma_f32_32x32x16_bf16 v[4:19], v[172:175], v[162:165], v[4:19]
	v_mfma_f32_32x32x16_bf16 v[68:83], v[172:175], v[168:171], v[68:83]
	v_mfma_f32_32x32x16_bf16 v[20:35], v[176:179], v[162:165], v[20:35]
	v_mfma_f32_32x32x16_bf16 v[84:99], v[176:179], v[168:171], v[84:99]
	v_mfma_f32_32x32x16_bf16 v[36:51], v[180:183], v[162:165], v[36:51]
	v_mfma_f32_32x32x16_bf16 v[100:115], v[180:183], v[168:171], v[100:115]
	v_mfma_f32_32x32x16_bf16 v[52:67], v[184:187], v[162:165], v[52:67]
	v_mfma_f32_32x32x16_bf16 v[116:131], v[184:187], v[168:171], v[116:131]
	ds_read_b128 v[162:165], v213 offset:32768
	ds_read_b128 v[168:171], v213 offset:36864
	ds_read_b128 v[172:175], v217 offset:32768
	ds_read_b128 v[176:179], v217 offset:36864
	ds_read_b128 v[180:183], v217 offset:49152
	ds_read_b128 v[184:187], v217 offset:53248
	s_waitcnt lgkmcnt(6)
	v_mfma_f32_32x32x16_bf16 v[4:19], v[140:143], v[132:135], v[4:19]
	v_mfma_f32_32x32x16_bf16 v[68:83], v[140:143], v[136:139], v[68:83]
	v_mfma_f32_32x32x16_bf16 v[20:35], v[144:147], v[132:135], v[20:35]
	v_mfma_f32_32x32x16_bf16 v[84:99], v[144:147], v[136:139], v[84:99]
	v_mfma_f32_32x32x16_bf16 v[36:51], v[148:151], v[132:135], v[36:51]
	v_mfma_f32_32x32x16_bf16 v[100:115], v[148:151], v[136:139], v[100:115]
	v_mfma_f32_32x32x16_bf16 v[52:67], v[158:161], v[132:135], v[52:67]
	v_mfma_f32_32x32x16_bf16 v[116:131], v[158:161], v[136:139], v[116:131]
	s_waitcnt lgkmcnt(0)
	v_mfma_f32_32x32x16_bf16 v[4:19], v[172:175], v[162:165], v[4:19]
	v_mfma_f32_32x32x16_bf16 v[68:83], v[172:175], v[168:171], v[68:83]
	v_mfma_f32_32x32x16_bf16 v[20:35], v[176:179], v[162:165], v[20:35]
	v_mfma_f32_32x32x16_bf16 v[84:99], v[176:179], v[168:171], v[84:99]
	v_mfma_f32_32x32x16_bf16 v[36:51], v[180:183], v[162:165], v[36:51]
	v_mfma_f32_32x32x16_bf16 v[100:115], v[180:183], v[168:171], v[100:115]
	v_mfma_f32_32x32x16_bf16 v[52:67], v[184:187], v[162:165], v[52:67]
	v_mfma_f32_32x32x16_bf16 v[116:131], v[184:187], v[168:171], v[116:131]
	s_waitcnt vmcnt(0) lgkmcnt(0)
	s_barrier
; #define MFMA32(a, b, c) __builtin_amdgcn_mfma_f32_32x32x16_bf16((a), (b), (c), 0, 0, 0)
; template <bool SWAP, class Epi>
; DI void gemm_tile(const u16* __restrict__ A, int lda, const u16* __restrict__ Bw, int ldb, int K, char* lds, Epi epi) {
;     ...
;   auto compute = [&](int st) {
;     const char* as = lds + st * GEMM_STAGE;
;     const char* bs = as + 36864;
; #pragma unroll
;     for (int ks = 0; ks < 4; ++ks) {
;       bf16x8 af[2], bfr[2];
; #pragma unroll
;       for (int mi = 0; mi < 2; ++mi) af[mi] = *(const bf16x8*)(as + ((wm * 64 + mi * 32 + r) * 72 + ks * 16 + 8 * h) * 2);
; #pragma unroll
;       for (int ni = 0; ni < 2; ++ni) bfr[ni] = *(const bf16x8*)(bs + ((wn * 64 + ni * 32 + r) * 72 + ks * 16 + 8 * h) * 2);
; #pragma unroll
;       for (int mi = 0; mi < 2; ++mi)
; #pragma unroll
;         for (int ni = 0; ni < 2; ++ni) {
;           if (SWAP) acc[mi][ni] = MFMA32(bfr[ni], af[mi], acc[mi][ni]);
;           else acc[mi][ni] = MFMA32(af[mi], bfr[ni], acc[mi][ni]);
;         }
;     }
;   };
;   gload(0, ra0, rb0);
;   lstore(0, ra0, rb0);
;   gload(1, ra1, rb1);
;   __syncthreads();
;   for (int kt = 0; kt < nk; kt += 2) {
;     if (kt + 2 < nk) gload(kt + 2, ra0, rb0);
;     compute(0);
;     lstore(1, ra1, rb1);
;     __syncthreads();
;     if (kt + 3 < nk) gload(kt + 3, ra1, rb1);
;     compute(1);
;     if (kt + 2 < nk) lstore(0, ra0, rb0);
;     __syncthreads();
	ds_read_b128 v[132:135], v210 offset:0
	ds_read_b128 v[136:139], v210 offset:4096
	ds_read_b128 v[140:143], v214 offset:0
	ds_read_b128 v[144:147], v214 offset:4096
	ds_read_b128 v[148:151], v214 offset:16384
	ds_read_b128 v[158:161], v214 offset:20480
	s_mov_b32 m0, s45
	s_nop 0
	global_load_lds_dwordx4 v208, s[68:69]
	global_load_lds_dwordx4 v209, s[70:71] offset:1024
	global_load_lds_dwordx4 v208, s[72:73] offset:2048
	global_load_lds_dwordx4 v209, s[74:75] offset:3072
	ds_read_b128 v[162:165], v211 offset:0
	ds_read_b128 v[168:171], v211 offset:4096
	ds_read_b128 v[172:175], v215 offset:0
	ds_read_b128 v[176:179], v215 offset:4096
	ds_read_b128 v[180:183], v215 offset:16384
	ds_read_b128 v[184:187], v215 offset:20480
	s_waitcnt lgkmcnt(6)
	v_mfma_f32_32x32x16_bf16 v[4:19], v[140:143], v[132:135], v[4:19]
	v_mfma_f32_32x32x16_bf16 v[68:83], v[140:143], v[136:139], v[68:83]
	v_mfma_f32_32x32x16_bf16 v[20:35], v[144:147], v[132:135], v[20:35]
	v_mfma_f32_32x32x16_bf16 v[84:99], v[144:147], v[136:139], v[84:99]
	v_mfma_f32_32x32x16_bf16 v[36:51], v[148:151], v[132:135], v[36:51]
	v_mfma_f32_32x32x16_bf16 v[100:115], v[148:151], v[136:139], v[100:115]
	v_mfma_f32_32x32x16_bf16 v[52:67], v[158:161], v[132:135], v[52:67]
	v_mfma_f32_32x32x16_bf16 v[116:131], v[158:161], v[136:139], v[116:131]
	s_mov_b32 m0, s47
	s_nop 0
	global_load_lds_dwordx4 v208, s[76:77]
	global_load_lds_dwordx4 v209, s[78:79] offset:1024
	global_load_lds_dwordx4 v208, s[80:81] offset:2048
	global_load_lds_dwordx4 v209, s[82:83] offset:3072
	v_add_u32_e32 v208, 0x80, v208
	v_add_u32_e32 v209, 0x80, v209
	ds_read_b128 v[132:135], v212 offset:0
	ds_read_b128 v[136:139], v212 offset:4096
	ds_read_b128 v[140:143], v216 offset:0
	ds_read_b128 v[144:147], v216 offset:4096
	ds_read_b128 v[148:151], v216 offset:16384
	ds_read_b128 v[158:161], v216 offset:20480
	s_waitcnt lgkmcnt(6)
	v_mfma_f32_32x32x16_bf16 v[4:19], v[172:175], v[162:165], v[4:19]
	v_mfma_f32_32x32x16_bf16 v[68:83], v[172:175], v[168:171], v[68:83]
	v_mfma_f32_32x32x16_bf16 v[20:35], v[176:179], v[162:165], v[20:35]
	v_mfma_f32_32x32x16_bf16 v[84:99], v[176:179], v[168:171], v[84:99]
	v_mfma_f32_32x32x16_bf16 v[36:51], v[180:183], v[162:165], v[36:51]
	v_mfma_f32_32x32x16_bf16 v[100:115], v[180:183], v[168:171], v[100:115]
	v_mfma_f32_32x32x16_bf16 v[52:67], v[184:187], v[162:165], v[52:67]
	v_mfma_f32_32x32x16_bf16 v[116:131], v[184:187], v[168:171], v[116:131]
	ds_read_b128 v[162:165], v213 offset:0
	ds_read_b128 v[168:171], v213 offset:4096
	ds_read_b128 v[172:175], v217 offset:0
	ds_read_b128 v[176:179], v217 offset:4096
	ds_read_b128 v[180:183], v217 offset:16384
	ds_read_b128 v[184:187], v217 offset:20480
	s_waitcnt lgkmcnt(6)
	v_mfma_f32_32x32x16_bf16 v[4:19], v[140:143], v[132:135], v[4:19]
	v_mfma_f32_32x32x16_bf16 v[68:83], v[140:143], v[136:139], v[68:83]
	v_mfma_f32_32x32x16_bf16 v[20:35], v[144:147], v[132:135], v[20:35]
	v_mfma_f32_32x32x16_bf16 v[84:99], v[144:147], v[136:139], v[84:99]
	v_mfma_f32_32x32x16_bf16 v[36:51], v[148:151], v[132:135], v[36:51]
	v_mfma_f32_32x32x16_bf16 v[100:115], v[148:151], v[136:139], v[100:115]
	v_mfma_f32_32x32x16_bf16 v[52:67], v[158:161], v[132:135], v[52:67]
	v_mfma_f32_32x32x16_bf16 v[116:131], v[158:161], v[136:139], v[116:131]
	s_waitcnt lgkmcnt(0)
	v_mfma_f32_32x32x16_bf16 v[4:19], v[172:175], v[162:165], v[4:19]
	v_mfma_f32_32x32x16_bf16 v[68:83], v[172:175], v[168:171], v[68:83]
	v_mfma_f32_32x32x16_bf16 v[20:35], v[176:179], v[162:165], v[20:35]
	v_mfma_f32_32x32x16_bf16 v[84:99], v[176:179], v[168:171], v[84:99]
	v_mfma_f32_32x32x16_bf16 v[36:51], v[180:183], v[162:165], v[36:51]
	v_mfma_f32_32x32x16_bf16 v[100:115], v[180:183], v[168:171], v[100:115]
	v_mfma_f32_32x32x16_bf16 v[52:67], v[184:187], v[162:165], v[52:67]
	v_mfma_f32_32x32x16_bf16 v[116:131], v[184:187], v[168:171], v[116:131]
	s_waitcnt vmcnt(0) lgkmcnt(0)
	s_barrier
	ds_read_b128 v[132:135], v210 offset:32768
	ds_read_b128 v[136:139], v210 offset:36864
	ds_read_b128 v[140:143], v214 offset:32768
	ds_read_b128 v[144:147], v214 offset:36864
	ds_read_b128 v[148:151], v214 offset:49152
	ds_read_b128 v[158:161], v214 offset:53248
	ds_read_b128 v[162:165], v211 offset:32768
	ds_read_b128 v[168:171], v211 offset:36864
	ds_read_b128 v[172:175], v215 offset:32768
	ds_read_b128 v[176:179], v215 offset:36864
	ds_read_b128 v[180:183], v215 offset:49152
	ds_read_b128 v[184:187], v215 offset:53248
	s_waitcnt lgkmcnt(6)
	v_mfma_f32_32x32x16_bf16 v[4:19], v[140:143], v[132:135], v[4:19]
	v_mfma_f32_32x32x16_bf16 v[68:83], v[140:143], v[136:139], v[68:83]
	v_mfma_f32_32x32x16_bf16 v[20:35], v[144:147], v[132:135], v[20:35]
	v_mfma_f32_32x32x16_bf16 v[84:99], v[144:147], v[136:139], v[84:99]
	v_mfma_f32_32x32x16_bf16 v[36:51], v[148:151], v[132:135], v[36:51]
	v_mfma_f32_32x32x16_bf16 v[100:115], v[148:151], v[136:139], v[100:115]
	v_mfma_f32_32x32x16_bf16 v[52:67], v[158:161], v[132:135], v[52:67]
	v_mfma_f32_32x32x16_bf16 v[116:131], v[158:161], v[136:139], v[116:131]
	ds_read_b128 v[132:135], v212 offset:32768
	ds_read_b128 v[136:139], v212 offset:36864
	ds_read_b128 v[140:143], v216 offset:32768
	ds_read_b128 v[144:147], v216 offset:36864
	ds_read_b128 v[148:151], v216 offset:49152
	ds_read_b128 v[158:161], v216 offset:53248
	s_waitcnt lgkmcnt(6)
; #define MFMA32(a, b, c) __builtin_amdgcn_mfma_f32_32x32x16_bf16((a), (b), (c), 0, 0, 0)
; template <bool SWAP, class Epi>
; DI void gemm_tile(const u16* __restrict__ A, int lda, const u16* __restrict__ Bw, int ldb, int K, char* lds, Epi epi) {
;     ...
;   auto gload = [&](int kt, u32x4* ra, u32x4* rb) {
; #pragma unroll
;     for (int j = 0; j < 4; ++j) ra[j] = *(const u32x4*)(ap + (size_t)(64 * j) * lda + kt * 64);
; #pragma unroll
;     for (int j = 0; j < 2; ++j) rb[j] = *(const u32x4*)(bp + (size_t)(64 * j) * ldb + kt * 64);
;   };
;     ...
;     for (int ks = 0; ks < 4; ++ks) {
;       bf16x8 af[2], bfr[2];
; #pragma unroll
;       for (int mi = 0; mi < 2; ++mi) af[mi] = *(const bf16x8*)(as + ((wm * 64 + mi * 32 + r) * 72 + ks * 16 + 8 * h) * 2);
; #pragma unroll
;       for (int ni = 0; ni < 2; ++ni) bfr[ni] = *(const bf16x8*)(bs + ((wn * 64 + ni * 32 + r) * 72 + ks * 16 + 8 * h) * 2);
; #pragma unroll
;       for (int mi = 0; mi < 2; ++mi)
; #pragma unroll
;         for (int ni = 0; ni < 2; ++ni) {
;           if (SWAP) acc[mi][ni] = MFMA32(bfr[ni], af[mi], acc[mi][ni]);
;           else acc[mi][ni] = MFMA32(af[mi], bfr[ni], acc[mi][ni]);
;         }
	v_mfma_f32_32x32x16_bf16 v[4:19], v[172:175], v[162:165], v[4:19]
	v_mfma_f32_32x32x16_bf16 v[68:83], v[172:175], v[168:171], v[68:83]
	v_mfma_f32_32x32x16_bf16 v[20:35], v[176:179], v[162:165], v[20:35]
	v_mfma_f32_32x32x16_bf16 v[84:99], v[176:179], v[168:171], v[84:99]
	v_mfma_f32_32x32x16_bf16 v[36:51], v[180:183], v[162:165], v[36:51]
	v_mfma_f32_32x32x16_bf16 v[100:115], v[180:183], v[168:171], v[100:115]
	v_mfma_f32_32x32x16_bf16 v[52:67], v[184:187], v[162:165], v[52:67]
	v_mfma_f32_32x32x16_bf16 v[116:131], v[184:187], v[168:171], v[116:131]
	ds_read_b128 v[162:165], v213 offset:32768
	ds_read_b128 v[168:171], v213 offset:36864
	ds_read_b128 v[172:175], v217 offset:32768
	ds_read_b128 v[176:179], v217 offset:36864
	ds_read_b128 v[180:183], v217 offset:49152
	ds_read_b128 v[184:187], v217 offset:53248
	s_waitcnt lgkmcnt(6)
	v_mfma_f32_32x32x16_bf16 v[4:19], v[140:143], v[132:135], v[4:19]
	v_mfma_f32_32x32x16_bf16 v[68:83], v[140:143], v[136:139], v[68:83]
	v_mfma_f32_32x32x16_bf16 v[20:35], v[144:147], v[132:135], v[20:35]
	v_mfma_f32_32x32x16_bf16 v[84:99], v[144:147], v[136:139], v[84:99]
	v_mfma_f32_32x32x16_bf16 v[36:51], v[148:151], v[132:135], v[36:51]
	v_mfma_f32_32x32x16_bf16 v[100:115], v[148:151], v[136:139], v[100:115]
	v_mfma_f32_32x32x16_bf16 v[52:67], v[158:161], v[132:135], v[52:67]
	v_mfma_f32_32x32x16_bf16 v[116:131], v[158:161], v[136:139], v[116:131]
	s_waitcnt lgkmcnt(0)
	v_mfma_f32_32x32x16_bf16 v[4:19], v[172:175], v[162:165], v[4:19]
	v_mfma_f32_32x32x16_bf16 v[68:83], v[172:175], v[168:171], v[68:83]
	v_mfma_f32_32x32x16_bf16 v[20:35], v[176:179], v[162:165], v[20:35]
	v_mfma_f32_32x32x16_bf16 v[84:99], v[176:179], v[168:171], v[84:99]
	v_mfma_f32_32x32x16_bf16 v[36:51], v[180:183], v[162:165], v[36:51]
	v_mfma_f32_32x32x16_bf16 v[100:115], v[180:183], v[168:171], v[100:115]
	v_mfma_f32_32x32x16_bf16 v[52:67], v[184:187], v[162:165], v[52:67]
	v_mfma_f32_32x32x16_bf16 v[116:131], v[184:187], v[168:171], v[116:131]
	s_waitcnt lgkmcnt(0)
	s_barrier
	s_cmp_gt_u32 s41, 5
	s_cbranch_scc1 .Lpp_nopf
	s_add_i32 s0, s101, 32
	s_cmpk_ge_u32 s0, 0xc6
	s_cbranch_scc1 .Lpp_nopf
	s_mul_i32 s1, s0, 0x5556
	s_lshr_b32 s1, s1, 16
	s_mul_i32 s4, s1, 3
	s_sub_i32 s0, s0, s4
	s_mul_i32 s0, s0, 6
	s_add_i32 s0, s0, s41
	s_lshl_b32 s4, s0, 1
	s_cmp_gt_u32 s0, 1
	s_cselect_b32 s5, 4, 0
	s_add_i32 s0, s4, s5
	v_readlane_b32 s4, v241, 26
	v_readlane_b32 s5, v241, 27
	s_lshl_b32 s1, s1, 19
	s_add_u32 s4, s4, s1
	s_addc_u32 s5, s5, 0
	s_lshl_b32 s0, s0, 18
	s_add_u32 s6, s18, s0
	s_addc_u32 s7, s19, 0
	s_lshl_b32 s0, s3, 16
	s_add_u32 s68, s4, s0
	s_addc_u32 s69, s5, 0
	s_add_u32 s70, s68, 0x3c00
	s_addc_u32 s71, s69, 0
	s_add_u32 s72, s70, 0x3c00
	s_addc_u32 s73, s71, 0
	s_add_u32 s74, s72, 0x3c00
	s_addc_u32 s75, s73, 0
	s_add_u32 s76, s6, s0
	s_addc_u32 s77, s7, 0
	s_add_u32 s78, s76, 0x3c00
	s_addc_u32 s79, s77, 0
	s_add_u32 s80, s78, 0x3c00
	s_addc_u32 s81, s79, 0
	s_add_u32 s82, s80, 0x3c00
	s_addc_u32 s83, s81, 0
	v_mov_b32_e32 v208, v220
	v_xor_b32_e32 v209, 64, v220
	s_mov_b32 m0, s44
	s_nop 0
	global_load_lds_dwordx4 v208, s[68:69]
	global_load_lds_dwordx4 v209, s[70:71] offset:1024
	global_load_lds_dwordx4 v208, s[72:73] offset:2048
	global_load_lds_dwordx4 v209, s[74:75] offset:3072
	s_mov_b32 m0, s46
	s_nop 0
	global_load_lds_dwordx4 v208, s[76:77]
	global_load_lds_dwordx4 v209, s[78:79] offset:1024
	global_load_lds_dwordx4 v208, s[80:81] offset:2048
	global_load_lds_dwordx4 v209, s[82:83] offset:3072
	s_mov_b32 s100, 1
; DI unsigned pk2(float a, float b) { f32x2 v = {a, b}; return __builtin_bit_cast(unsigned, __builtin_convertvector(v, bf2_t)); }
; DI void store_rowmajor(u16* dst, const f32x16& a, int h, float sc) {
; #pragma unroll
;   for (int kp = 0; kp < 2; ++kp) {
;     const int g = 2 * kp;
;     unsigned ax = pk2(a[4 * g] * sc, a[4 * g + 1] * sc), ay = pk2(a[4 * g + 2] * sc, a[4 * g + 3] * sc);
;     unsigned bx = pk2(a[4 * g + 4] * sc, a[4 * g + 5] * sc), by = pk2(a[4 * g + 6] * sc, a[4 * g + 7] * sc);
;     const u32x2 rx = __builtin_amdgcn_permlane32_swap(ax, bx, false, false);
;     const u32x2 ry = __builtin_amdgcn_permlane32_swap(ay, by, false, false);
;     const u32x4 v = {rx[0], ry[0], rx[1], ry[1]};
;     *(u32x4*)(dst + 8 * (g + h)) = v;
;   }
; }
; DI void inproj_tile(const Params& p, int l, int mt, int nt, char* lds) {
;     ...
;     gemm_tile<true>(A, DM, Bw, DM, DM, lds, [&](int mi, int ni, const f32x16& a) {
;       const int tok = m0 + wm * 64 + mi * 32 + r;
;       store_rowmajor(p.H + (size_t)tok * LDH + nt * 128 + wn * 64 + ni * 32, a, h, 1.f);
.Lpp_nopf:
	s_nop 7
	s_nop 7
	v_cvt_pk_bf16_f32 v224, v4, v5
	v_cvt_pk_bf16_f32 v225, v6, v7
	v_cvt_pk_bf16_f32 v226, v8, v9
	v_cvt_pk_bf16_f32 v227, v10, v11
	s_nop 1
	v_permlane32_swap_b32_e32 v224, v226
	v_permlane32_swap_b32_e32 v225, v227
	s_nop 0
	global_store_dwordx4 v218, v[224:227], s[8:9]
	v_cvt_pk_bf16_f32 v228, v12, v13
	v_cvt_pk_bf16_f32 v229, v14, v15
	v_cvt_pk_bf16_f32 v230, v16, v17
	v_cvt_pk_bf16_f32 v231, v18, v19
	s_nop 1
	v_permlane32_swap_b32_e32 v228, v230
	v_permlane32_swap_b32_e32 v229, v231
	s_nop 0
	global_store_dwordx4 v218, v[228:231], s[8:9] offset:32
	v_cvt_pk_bf16_f32 v224, v68, v69
	v_cvt_pk_bf16_f32 v225, v70, v71
	v_cvt_pk_bf16_f32 v226, v72, v73
	v_cvt_pk_bf16_f32 v227, v74, v75
	s_nop 1
	v_permlane32_swap_b32_e32 v224, v226
	v_permlane32_swap_b32_e32 v225, v227
	s_nop 0
	global_store_dwordx4 v219, v[224:227], s[8:9]
	v_cvt_pk_bf16_f32 v228, v76, v77
	v_cvt_pk_bf16_f32 v229, v78, v79
	v_cvt_pk_bf16_f32 v230, v80, v81
	v_cvt_pk_bf16_f32 v231, v82, v83
	s_nop 1
	v_permlane32_swap_b32_e32 v228, v230
	v_permlane32_swap_b32_e32 v229, v231
	s_nop 0
	global_store_dwordx4 v219, v[228:231], s[8:9] offset:32
	v_cvt_pk_bf16_f32 v224, v20, v21
	v_cvt_pk_bf16_f32 v225, v22, v23
	v_cvt_pk_bf16_f32 v226, v24, v25
	v_cvt_pk_bf16_f32 v227, v26, v27
	s_nop 1
	v_permlane32_swap_b32_e32 v224, v226
	v_permlane32_swap_b32_e32 v225, v227
	s_nop 0
	global_store_dwordx4 v218, v[224:227], s[8:9] offset:64
	v_cvt_pk_bf16_f32 v228, v28, v29
	v_cvt_pk_bf16_f32 v229, v30, v31
	v_cvt_pk_bf16_f32 v230, v32, v33
	v_cvt_pk_bf16_f32 v231, v34, v35
	s_nop 1
	v_permlane32_swap_b32_e32 v228, v230
	v_permlane32_swap_b32_e32 v229, v231
	s_nop 0
	global_store_dwordx4 v218, v[228:231], s[8:9] offset:96
	v_cvt_pk_bf16_f32 v224, v84, v85
	v_cvt_pk_bf16_f32 v225, v86, v87
	v_cvt_pk_bf16_f32 v226, v88, v89
	v_cvt_pk_bf16_f32 v227, v90, v91
	s_nop 1
	v_permlane32_swap_b32_e32 v224, v226
	v_permlane32_swap_b32_e32 v225, v227
	s_nop 0
	global_store_dwordx4 v219, v[224:227], s[8:9] offset:64
	v_cvt_pk_bf16_f32 v228, v92, v93
	v_cvt_pk_bf16_f32 v229, v94, v95
	v_cvt_pk_bf16_f32 v230, v96, v97
	v_cvt_pk_bf16_f32 v231, v98, v99
	s_nop 1
	v_permlane32_swap_b32_e32 v228, v230
	v_permlane32_swap_b32_e32 v229, v231
	s_nop 0
	global_store_dwordx4 v219, v[228:231], s[8:9] offset:96
	v_cvt_pk_bf16_f32 v224, v36, v37
	v_cvt_pk_bf16_f32 v225, v38, v39
	v_cvt_pk_bf16_f32 v226, v40, v41
	v_cvt_pk_bf16_f32 v227, v42, v43
	s_nop 1
	v_permlane32_swap_b32_e32 v224, v226
	v_permlane32_swap_b32_e32 v225, v227
	s_nop 0
	global_store_dwordx4 v218, v[224:227], s[8:9] offset:256
	v_cvt_pk_bf16_f32 v228, v44, v45
	v_cvt_pk_bf16_f32 v229, v46, v47
	v_cvt_pk_bf16_f32 v230, v48, v49
	v_cvt_pk_bf16_f32 v231, v50, v51
	s_nop 1
	v_permlane32_swap_b32_e32 v228, v230
	v_permlane32_swap_b32_e32 v229, v231
	s_nop 0
	global_store_dwordx4 v218, v[228:231], s[8:9] offset:288
	v_cvt_pk_bf16_f32 v224, v100, v101
	v_cvt_pk_bf16_f32 v225, v102, v103
	v_cvt_pk_bf16_f32 v226, v104, v105
	v_cvt_pk_bf16_f32 v227, v106, v107
	s_nop 1
	v_permlane32_swap_b32_e32 v224, v226
	v_permlane32_swap_b32_e32 v225, v227
	s_nop 0
	global_store_dwordx4 v219, v[224:227], s[8:9] offset:256
	v_cvt_pk_bf16_f32 v228, v108, v109
	v_cvt_pk_bf16_f32 v229, v110, v111
	v_cvt_pk_bf16_f32 v230, v112, v113
	v_cvt_pk_bf16_f32 v231, v114, v115
	s_nop 1
	v_permlane32_swap_b32_e32 v228, v230
	v_permlane32_swap_b32_e32 v229, v231
	s_nop 0
	global_store_dwordx4 v219, v[228:231], s[8:9] offset:288
	v_cvt_pk_bf16_f32 v224, v52, v53
	v_cvt_pk_bf16_f32 v225, v54, v55
	v_cvt_pk_bf16_f32 v226, v56, v57
	v_cvt_pk_bf16_f32 v227, v58, v59
	s_nop 1
	v_permlane32_swap_b32_e32 v224, v226
	v_permlane32_swap_b32_e32 v225, v227
	s_nop 0
	global_store_dwordx4 v218, v[224:227], s[8:9] offset:320
	v_cvt_pk_bf16_f32 v228, v60, v61
	v_cvt_pk_bf16_f32 v229, v62, v63
	v_cvt_pk_bf16_f32 v230, v64, v65
	v_cvt_pk_bf16_f32 v231, v66, v67
	s_nop 1
	v_permlane32_swap_b32_e32 v228, v230
	v_permlane32_swap_b32_e32 v229, v231
	s_nop 0
	global_store_dwordx4 v218, v[228:231], s[8:9] offset:352
	v_cvt_pk_bf16_f32 v224, v116, v117
	v_cvt_pk_bf16_f32 v225, v118, v119
	v_cvt_pk_bf16_f32 v226, v120, v121
	v_cvt_pk_bf16_f32 v227, v122, v123
	s_nop 1
	v_permlane32_swap_b32_e32 v224, v226
	v_permlane32_swap_b32_e32 v225, v227
	s_nop 0
	global_store_dwordx4 v219, v[224:227], s[8:9] offset:320
	v_cvt_pk_bf16_f32 v228, v124, v125
	v_cvt_pk_bf16_f32 v229, v126, v127
	v_cvt_pk_bf16_f32 v230, v128, v129
	v_cvt_pk_bf16_f32 v231, v130, v131
	s_nop 1
	v_permlane32_swap_b32_e32 v228, v230
	v_permlane32_swap_b32_e32 v229, v231
	s_nop 0
	global_store_dwordx4 v219, v[228:231], s[8:9] offset:352
	s_branch .LBB0_323
